# stream GEMM S1.L: second LDS-DMA piece of stage a issued after the B1 fragment reads (covers their latency), 6 sites in 3 loops, on v25
# baseline (speedup 1.0000x reference)
; template <class EPI>
; DI void gemm_stream(const u16* __restrict__ A, const u16* __restrict__ Bt, const int K, const int nM, const int nN,
;                     const int bid, const int nb, const int tid, EPI epi) {
;     ...
;     for (int t = 0; t < nt; t += 2) {
;       const bool inside = (t + 2 < nt);
;       const int brs = inside ? brow : brow2, bcs = inside ? bcol : bcol2, t2 = inside ? t + 2 : 0;
.LBB0_32:
	s_add_i32 s11, s10, 2
	ds_read_b128 v[132:135], v159
	ds_read_b128 v[136:139], v160
	ds_read_b128 v[180:183], v161
	ds_read_b128 v[184:187], v162
	s_cmpk_lt_u32 s10, 0x56
	s_cselect_b32 s12, s8, s5
	s_cselect_b32 s13, s7, s6
	s_cselect_b32 s14, s9, 0
	s_mulk_i32 s13, 0x1600
	s_mulk_i32 s12, 0x1600
	s_or_b32 s15, s14, 64
	s_add_i32 s17, s12, s14
	s_add_i32 s18, s13, 0xb0000
	s_add_i32 s16, s13, s14
	s_add_i32 s13, s15, s13
	s_add_i32 s12, s15, s12
	s_lshl_b32 s17, s17, 1
	s_add_i32 s14, s18, s14
	s_add_i32 s18, s18, s15
	s_addk_i32 s9, 0x80
	s_lshl_b32 s16, s16, 1
	s_lshl_b32 s19, s13, 1
	s_lshl_b32 s13, s12, 1
	s_lshl_b32 s14, s14, 1
	s_add_i32 s15, s17, 0x160000
	s_lshl_b32 s12, s18, 1
	s_cmpk_gt_u32 s10, 0x55
	v_readfirstlane_b32 s10, v163
	v_add_u32_e32 v131, 0xfff50000, v130
	s_mov_b32 m0, s10
	v_readfirstlane_b32 s10, v165
	ds_read_b128 v[188:191], v157
	ds_read_b128 v[192:195], v157 offset:1024
	ds_read_b128 v[196:199], v157 offset:2048
	ds_read_b128 v[200:203], v157 offset:3072
	ds_read_b128 v[204:207], v157 offset:4096
	ds_read_b128 v[208:211], v157 offset:5120
	ds_read_b128 v[212:215], v157 offset:6144
	ds_read_b128 v[216:219], v157 offset:7168
	global_load_lds_dwordx4 v131, s[76:77]
	s_waitcnt lgkmcnt(8)
	ds_read_b128 v[220:223], v166
	ds_read_b128 v[242:245], v167
	ds_read_b128 v[246:249], v168
	ds_read_b128 v[250:253], v169
	s_mov_b32 m0, s10
	s_nop 0
	global_load_lds_dwordx4 v130, s[76:77]
	s_waitcnt vmcnt(8)
	s_waitcnt lgkmcnt(0)
	s_barrier
	v_mfma_f32_16x16x32_bf16 v[126:129], v[132:135], v[188:191], v[126:129]
	v_mfma_f32_16x16x32_bf16 v[122:125], v[180:183], v[188:191], v[122:125]
	v_mfma_f32_16x16x32_bf16 v[118:121], v[132:135], v[196:199], v[118:121]
	v_mfma_f32_16x16x32_bf16 v[114:117], v[180:183], v[196:199], v[114:117]
	v_mfma_f32_16x16x32_bf16 v[110:113], v[132:135], v[204:207], v[110:113]
	v_mfma_f32_16x16x32_bf16 v[106:109], v[180:183], v[204:207], v[106:109]
	v_mfma_f32_16x16x32_bf16 v[102:105], v[132:135], v[212:215], v[102:105]
	v_mfma_f32_16x16x32_bf16 v[98:101], v[180:183], v[212:215], v[98:101]
	v_mfma_f32_16x16x32_bf16 v[126:129], v[136:139], v[192:195], v[126:129]
	v_mfma_f32_16x16x32_bf16 v[122:125], v[184:187], v[192:195], v[122:125]
	v_mfma_f32_16x16x32_bf16 v[118:121], v[136:139], v[200:203], v[118:121]
	v_mfma_f32_16x16x32_bf16 v[114:117], v[184:187], v[200:203], v[114:117]
	v_mfma_f32_16x16x32_bf16 v[110:113], v[136:139], v[208:211], v[110:113]
	v_mfma_f32_16x16x32_bf16 v[106:109], v[184:187], v[208:211], v[106:109]
	v_mfma_f32_16x16x32_bf16 v[102:105], v[136:139], v[216:219], v[102:105]
	v_mfma_f32_16x16x32_bf16 v[98:101], v[184:187], v[216:219], v[98:101]
	v_mfma_f32_16x16x32_bf16 v[94:97], v[220:223], v[188:191], v[94:97]
	v_mfma_f32_16x16x32_bf16 v[90:93], v[246:249], v[188:191], v[90:93]
	v_mfma_f32_16x16x32_bf16 v[86:89], v[220:223], v[196:199], v[86:89]
	v_mfma_f32_16x16x32_bf16 v[82:85], v[246:249], v[196:199], v[82:85]
	v_mfma_f32_16x16x32_bf16 v[78:81], v[220:223], v[204:207], v[78:81]
	v_mfma_f32_16x16x32_bf16 v[74:77], v[246:249], v[204:207], v[74:77]
	v_mfma_f32_16x16x32_bf16 v[70:73], v[220:223], v[212:215], v[70:73]
	v_mfma_f32_16x16x32_bf16 v[66:69], v[246:249], v[212:215], v[66:69]
	v_mfma_f32_16x16x32_bf16 v[94:97], v[242:245], v[192:195], v[94:97]
	v_mfma_f32_16x16x32_bf16 v[90:93], v[250:253], v[192:195], v[90:93]
	v_mfma_f32_16x16x32_bf16 v[86:89], v[242:245], v[200:203], v[86:89]
	v_mfma_f32_16x16x32_bf16 v[82:85], v[250:253], v[200:203], v[82:85]
	v_mfma_f32_16x16x32_bf16 v[78:81], v[242:245], v[208:211], v[78:81]
	v_mfma_f32_16x16x32_bf16 v[74:77], v[250:253], v[208:211], v[74:77]
	v_mfma_f32_16x16x32_bf16 v[70:73], v[242:245], v[216:219], v[70:73]
	v_mfma_f32_16x16x32_bf16 v[66:69], v[250:253], v[216:219], v[66:69]
	s_barrier
	v_readfirstlane_b32 s10, v144
	v_add_u32_e32 v131, s16, v142
	s_mov_b32 m0, s10
	v_readfirstlane_b32 s10, v145
	global_load_lds_dwordx4 v131, s[78:79]
	v_add_u32_e32 v131, s16, v143
	s_mov_b32 m0, s10
	s_nop 0
	global_load_lds_dwordx4 v131, s[78:79]
	v_readfirstlane_b32 s10, v0
	v_add_u32_e32 v131, s17, v142
	s_mov_b32 m0, s10
	v_readfirstlane_b32 s10, v146
	ds_read_b128 v[188:191], v157 offset:16384
	ds_read_b128 v[192:195], v157 offset:17408
	ds_read_b128 v[196:199], v157 offset:18432
	ds_read_b128 v[200:203], v157 offset:19456
	ds_read_b128 v[204:207], v157 offset:20480
	ds_read_b128 v[208:211], v157 offset:21504
	ds_read_b128 v[212:215], v157 offset:22528
	ds_read_b128 v[216:219], v157 offset:23552
	global_load_lds_dwordx4 v131, s[76:77]
	v_add_u32_e32 v131, s17, v143
	s_mov_b32 m0, s10
	s_nop 0
	global_load_lds_dwordx4 v131, s[76:77]
	v_readfirstlane_b32 s10, v147
	v_add_u32_e32 v131, s14, v142
	s_mov_b32 m0, s10
	v_readfirstlane_b32 s10, v148
	global_load_lds_dwordx4 v131, s[78:79]
	v_add_u32_e32 v131, s14, v143
	s_mov_b32 m0, s10
	s_nop 0
	global_load_lds_dwordx4 v131, s[78:79]
	s_waitcnt vmcnt(8)
	s_waitcnt lgkmcnt(0)
	s_barrier
	v_mfma_f32_16x16x32_bf16 v[62:65], v[132:135], v[188:191], v[62:65]
	v_mfma_f32_16x16x32_bf16 v[58:61], v[180:183], v[188:191], v[58:61]
	v_mfma_f32_16x16x32_bf16 v[54:57], v[132:135], v[196:199], v[54:57]
	v_mfma_f32_16x16x32_bf16 v[50:53], v[180:183], v[196:199], v[50:53]
	v_mfma_f32_16x16x32_bf16 v[46:49], v[132:135], v[204:207], v[46:49]
	v_mfma_f32_16x16x32_bf16 v[42:45], v[180:183], v[204:207], v[42:45]
	v_mfma_f32_16x16x32_bf16 v[38:41], v[132:135], v[212:215], v[38:41]
	v_mfma_f32_16x16x32_bf16 v[34:37], v[180:183], v[212:215], v[34:37]
	v_mfma_f32_16x16x32_bf16 v[62:65], v[136:139], v[192:195], v[62:65]
	v_mfma_f32_16x16x32_bf16 v[58:61], v[184:187], v[192:195], v[58:61]
	v_mfma_f32_16x16x32_bf16 v[54:57], v[136:139], v[200:203], v[54:57]
	v_mfma_f32_16x16x32_bf16 v[50:53], v[184:187], v[200:203], v[50:53]
	v_mfma_f32_16x16x32_bf16 v[46:49], v[136:139], v[208:211], v[46:49]
	v_mfma_f32_16x16x32_bf16 v[42:45], v[184:187], v[208:211], v[42:45]
	v_mfma_f32_16x16x32_bf16 v[38:41], v[136:139], v[216:219], v[38:41]
	v_mfma_f32_16x16x32_bf16 v[34:37], v[184:187], v[216:219], v[34:37]
	v_mfma_f32_16x16x32_bf16 v[30:33], v[220:223], v[188:191], v[30:33]
	v_mfma_f32_16x16x32_bf16 v[26:29], v[246:249], v[188:191], v[26:29]
	v_mfma_f32_16x16x32_bf16 v[22:25], v[220:223], v[196:199], v[22:25]
	v_mfma_f32_16x16x32_bf16 v[18:21], v[246:249], v[196:199], v[18:21]
	v_mfma_f32_16x16x32_bf16 v[14:17], v[220:223], v[204:207], v[14:17]
	v_mfma_f32_16x16x32_bf16 v[10:13], v[246:249], v[204:207], v[10:13]
	v_mfma_f32_16x16x32_bf16 v[6:9], v[220:223], v[212:215], v[6:9]
	v_mfma_f32_16x16x32_bf16 v[2:5], v[246:249], v[212:215], v[2:5]
	v_mfma_f32_16x16x32_bf16 v[30:33], v[242:245], v[192:195], v[30:33]
	v_mfma_f32_16x16x32_bf16 v[26:29], v[250:253], v[192:195], v[26:29]
	v_mfma_f32_16x16x32_bf16 v[22:25], v[242:245], v[200:203], v[22:25]
	v_mfma_f32_16x16x32_bf16 v[18:21], v[250:253], v[200:203], v[18:21]
	v_mfma_f32_16x16x32_bf16 v[14:17], v[242:245], v[208:211], v[14:17]
	v_mfma_f32_16x16x32_bf16 v[10:13], v[250:253], v[208:211], v[10:13]
	v_mfma_f32_16x16x32_bf16 v[6:9], v[242:245], v[216:219], v[6:9]
	v_mfma_f32_16x16x32_bf16 v[2:5], v[250:253], v[216:219], v[2:5]
	s_barrier
	ds_read_b128 v[132:135], v170
	ds_read_b128 v[136:139], v171
	ds_read_b128 v[180:183], v172
	ds_read_b128 v[184:187], v173
	v_readfirstlane_b32 s10, v149
	v_add_u32_e32 v131, s15, v142
	s_mov_b32 m0, s10
	v_readfirstlane_b32 s10, v150
	ds_read_b128 v[188:191], v157 offset:32768
	ds_read_b128 v[192:195], v157 offset:33792
	ds_read_b128 v[196:199], v157 offset:34816
	ds_read_b128 v[200:203], v157 offset:35840
	ds_read_b128 v[204:207], v157 offset:36864
	ds_read_b128 v[208:211], v157 offset:37888
	ds_read_b128 v[212:215], v157 offset:38912
	ds_read_b128 v[216:219], v157 offset:39936
	global_load_lds_dwordx4 v131, s[76:77]
	s_waitcnt lgkmcnt(8)
	ds_read_b128 v[220:223], v174
	ds_read_b128 v[242:245], v175
	ds_read_b128 v[246:249], v176
	ds_read_b128 v[250:253], v177
	v_add_u32_e32 v131, s15, v143
	s_mov_b32 m0, s10
	s_nop 0
	global_load_lds_dwordx4 v131, s[76:77]
	s_waitcnt vmcnt(8)
	s_waitcnt lgkmcnt(0)
	s_barrier
	v_mfma_f32_16x16x32_bf16 v[126:129], v[132:135], v[188:191], v[126:129]
	v_mfma_f32_16x16x32_bf16 v[122:125], v[180:183], v[188:191], v[122:125]
	v_mfma_f32_16x16x32_bf16 v[118:121], v[132:135], v[196:199], v[118:121]
	v_mfma_f32_16x16x32_bf16 v[114:117], v[180:183], v[196:199], v[114:117]
	v_mfma_f32_16x16x32_bf16 v[110:113], v[132:135], v[204:207], v[110:113]
	v_mfma_f32_16x16x32_bf16 v[106:109], v[180:183], v[204:207], v[106:109]
	v_mfma_f32_16x16x32_bf16 v[102:105], v[132:135], v[212:215], v[102:105]
	v_mfma_f32_16x16x32_bf16 v[98:101], v[180:183], v[212:215], v[98:101]
	v_mfma_f32_16x16x32_bf16 v[126:129], v[136:139], v[192:195], v[126:129]
	v_mfma_f32_16x16x32_bf16 v[122:125], v[184:187], v[192:195], v[122:125]
	v_mfma_f32_16x16x32_bf16 v[118:121], v[136:139], v[200:203], v[118:121]
	v_mfma_f32_16x16x32_bf16 v[114:117], v[184:187], v[200:203], v[114:117]
	v_mfma_f32_16x16x32_bf16 v[110:113], v[136:139], v[208:211], v[110:113]
	v_mfma_f32_16x16x32_bf16 v[106:109], v[184:187], v[208:211], v[106:109]
	v_mfma_f32_16x16x32_bf16 v[102:105], v[136:139], v[216:219], v[102:105]
	v_mfma_f32_16x16x32_bf16 v[98:101], v[184:187], v[216:219], v[98:101]
	v_mfma_f32_16x16x32_bf16 v[94:97], v[220:223], v[188:191], v[94:97]
	v_mfma_f32_16x16x32_bf16 v[90:93], v[246:249], v[188:191], v[90:93]
	v_mfma_f32_16x16x32_bf16 v[86:89], v[220:223], v[196:199], v[86:89]
	v_mfma_f32_16x16x32_bf16 v[82:85], v[246:249], v[196:199], v[82:85]
	v_mfma_f32_16x16x32_bf16 v[78:81], v[220:223], v[204:207], v[78:81]
	v_mfma_f32_16x16x32_bf16 v[74:77], v[246:249], v[204:207], v[74:77]
	v_mfma_f32_16x16x32_bf16 v[70:73], v[220:223], v[212:215], v[70:73]
	v_mfma_f32_16x16x32_bf16 v[66:69], v[246:249], v[212:215], v[66:69]
	v_mfma_f32_16x16x32_bf16 v[94:97], v[242:245], v[192:195], v[94:97]
	v_mfma_f32_16x16x32_bf16 v[90:93], v[250:253], v[192:195], v[90:93]
	v_mfma_f32_16x16x32_bf16 v[86:89], v[242:245], v[200:203], v[86:89]
	v_mfma_f32_16x16x32_bf16 v[82:85], v[250:253], v[200:203], v[82:85]
	v_mfma_f32_16x16x32_bf16 v[78:81], v[242:245], v[208:211], v[78:81]
	v_mfma_f32_16x16x32_bf16 v[74:77], v[250:253], v[208:211], v[74:77]
	v_mfma_f32_16x16x32_bf16 v[70:73], v[242:245], v[216:219], v[70:73]
	v_mfma_f32_16x16x32_bf16 v[66:69], v[250:253], v[216:219], v[66:69]
	s_barrier
; DI void gemm_resid(const u16* A, const u16* Bt, int K, const float* xin, float* xout, int bid, int nb, int tid) {
;     ...
;     for (int ai = 0; ai < 2; ++ai)
; #pragma unroll
;       for (int bj = 0; bj < 2; ++bj) {
;         float4 xi[4][2];
; #pragma unroll
;         for (int m = 0; m < 4; ++m)
; #pragma unroll
;           for (int n = 0; n < 2; ++n) xi[m][n] = *reinterpret_cast<const float4*>(xin + (size_t)ACC_ROW * 2048 + ACC_COL);
	v_readfirstlane_b32 s10, v151
	v_add_u32_e32 v131, s19, v142
	s_mov_b32 m0, s10
	v_readfirstlane_b32 s10, v152
	global_load_lds_dwordx4 v131, s[78:79]
	v_add_u32_e32 v131, s19, v143
	s_mov_b32 m0, s10
	s_nop 0
	global_load_lds_dwordx4 v131, s[78:79]
	v_readfirstlane_b32 s10, v153
	v_add_u32_e32 v131, s13, v142
	s_mov_b32 m0, s10
	v_readfirstlane_b32 s10, v154
	ds_read_b128 v[188:191], v157 offset:49152
	ds_read_b128 v[192:195], v157 offset:50176
	ds_read_b128 v[196:199], v157 offset:51200
	ds_read_b128 v[200:203], v157 offset:52224
	ds_read_b128 v[204:207], v157 offset:53248
	ds_read_b128 v[208:211], v157 offset:54272
	ds_read_b128 v[212:215], v157 offset:55296
	ds_read_b128 v[216:219], v157 offset:56320
	global_load_lds_dwordx4 v131, s[76:77]
	v_add_u32_e32 v131, s13, v143
	s_mov_b32 m0, s10
	s_nop 0
	global_load_lds_dwordx4 v131, s[76:77]
	v_readfirstlane_b32 s10, v155
	v_add_u32_e32 v131, s12, v142
	s_mov_b32 m0, s10
	v_readfirstlane_b32 s10, v156
	global_load_lds_dwordx4 v131, s[78:79]
	v_add_u32_e32 v131, s12, v143
	s_mov_b32 m0, s10
	s_nop 0
	global_load_lds_dwordx4 v131, s[78:79]
	s_waitcnt vmcnt(8)
	s_waitcnt lgkmcnt(0)
	s_barrier
	v_mfma_f32_16x16x32_bf16 v[62:65], v[132:135], v[188:191], v[62:65]
	v_mfma_f32_16x16x32_bf16 v[58:61], v[180:183], v[188:191], v[58:61]
	v_mfma_f32_16x16x32_bf16 v[54:57], v[132:135], v[196:199], v[54:57]
	v_mfma_f32_16x16x32_bf16 v[50:53], v[180:183], v[196:199], v[50:53]
	v_mfma_f32_16x16x32_bf16 v[46:49], v[132:135], v[204:207], v[46:49]
	v_mfma_f32_16x16x32_bf16 v[42:45], v[180:183], v[204:207], v[42:45]
	v_mfma_f32_16x16x32_bf16 v[38:41], v[132:135], v[212:215], v[38:41]
	v_mfma_f32_16x16x32_bf16 v[34:37], v[180:183], v[212:215], v[34:37]
	v_mfma_f32_16x16x32_bf16 v[62:65], v[136:139], v[192:195], v[62:65]
	v_mfma_f32_16x16x32_bf16 v[58:61], v[184:187], v[192:195], v[58:61]
	v_mfma_f32_16x16x32_bf16 v[54:57], v[136:139], v[200:203], v[54:57]
	v_mfma_f32_16x16x32_bf16 v[50:53], v[184:187], v[200:203], v[50:53]
	v_mfma_f32_16x16x32_bf16 v[46:49], v[136:139], v[208:211], v[46:49]
	v_mfma_f32_16x16x32_bf16 v[42:45], v[184:187], v[208:211], v[42:45]
	v_mfma_f32_16x16x32_bf16 v[38:41], v[136:139], v[216:219], v[38:41]
	v_mfma_f32_16x16x32_bf16 v[34:37], v[184:187], v[216:219], v[34:37]
	v_mfma_f32_16x16x32_bf16 v[30:33], v[220:223], v[188:191], v[30:33]
	v_mfma_f32_16x16x32_bf16 v[26:29], v[246:249], v[188:191], v[26:29]
	v_mfma_f32_16x16x32_bf16 v[22:25], v[220:223], v[196:199], v[22:25]
	v_mfma_f32_16x16x32_bf16 v[18:21], v[246:249], v[196:199], v[18:21]
	v_mfma_f32_16x16x32_bf16 v[14:17], v[220:223], v[204:207], v[14:17]
	v_mfma_f32_16x16x32_bf16 v[10:13], v[246:249], v[204:207], v[10:13]
	v_mfma_f32_16x16x32_bf16 v[6:9], v[220:223], v[212:215], v[6:9]
	v_mfma_f32_16x16x32_bf16 v[2:5], v[246:249], v[212:215], v[2:5]
	v_mfma_f32_16x16x32_bf16 v[30:33], v[242:245], v[192:195], v[30:33]
	v_mfma_f32_16x16x32_bf16 v[26:29], v[250:253], v[192:195], v[26:29]
	v_mfma_f32_16x16x32_bf16 v[22:25], v[242:245], v[200:203], v[22:25]
	v_mfma_f32_16x16x32_bf16 v[18:21], v[250:253], v[200:203], v[18:21]
	v_mfma_f32_16x16x32_bf16 v[14:17], v[242:245], v[208:211], v[14:17]
	v_mfma_f32_16x16x32_bf16 v[10:13], v[250:253], v[208:211], v[10:13]
	v_mfma_f32_16x16x32_bf16 v[6:9], v[242:245], v[216:219], v[6:9]
	v_mfma_f32_16x16x32_bf16 v[2:5], v[250:253], v[216:219], v[2:5]
	v_add_u32_e32 v130, 0x100, v130
	s_mov_b32 s10, s11
	s_barrier
	s_cbranch_scc0 .LBB0_32
	v_mov_b32_e32 v131, v239
	s_nop 0
	v_ashrrev_i32_e32 v130, 2, v131
	v_and_b32_e32 v130, 0xffffffc0, v130
	v_and_or_b32 v132, v131, 15, s8
	v_add_u32_e32 v130, v132, v130
	v_lshrrev_b32_e32 v132, 1, v131
	v_lshrrev_b32_e32 v131, 2, v131
	v_and_b32_e32 v132, 0x60, v132
	v_and_b32_e32 v131, 12, v131
	v_or3_b32 v132, v132, v131, s7
	v_ashrrev_i32_e32 v131, 31, v130
	v_ashrrev_i32_e32 v133, 31, v132
	v_lshlrev_b64 v[134:135], 13, v[130:131]
	v_lshl_add_u64 v[134:135], s[72:73], 0, v[134:135]
	v_lshlrev_b64 v[132:133], 2, v[132:133]
	v_lshl_add_u64 v[140:141], v[134:135], 0, v[132:133]
	v_or_b32_e32 v134, 16, v130
	v_ashrrev_i32_e32 v135, 31, v134
	v_lshlrev_b64 v[134:135], 13, v[134:135]
	v_lshl_add_u64 v[134:135], s[72:73], 0, v[134:135]
	v_lshl_add_u64 v[138:139], v[134:135], 0, v[132:133]
	v_or_b32_e32 v134, 32, v130
	v_ashrrev_i32_e32 v135, 31, v134
	v_lshlrev_b64 v[134:135], 13, v[134:135]
	v_lshl_add_u64 v[134:135], s[72:73], 0, v[134:135]
	v_lshl_add_u64 v[136:137], v[134:135], 0, v[132:133]
	v_or_b32_e32 v134, 48, v130
	v_ashrrev_i32_e32 v135, 31, v134
	v_lshlrev_b64 v[134:135], 13, v[134:135]
	v_lshl_add_u64 v[134:135], s[72:73], 0, v[134:135]
	v_lshl_add_u64 v[134:135], v[134:135], 0, v[132:133]
	global_load_dwordx4 v[180:183], v[140:141], off
	global_load_dwordx4 v[184:187], v[140:141], off offset:64
	global_load_dwordx4 v[188:191], v[138:139], off
	global_load_dwordx4 v[192:195], v[138:139], off offset:64
	global_load_dwordx4 v[196:199], v[136:137], off
	global_load_dwordx4 v[200:203], v[136:137], off offset:64
	global_load_dwordx4 v[204:207], v[134:135], off
	global_load_dwordx4 v[208:211], v[134:135], off offset:64
	s_waitcnt vmcnt(0)
; #define EPI_SCHED __builtin_amdgcn_sched_barrier(0)
; DI void gemm_resid(const u16* A, const u16* Bt, int K, const float* xin, float* xout, int bid, int nb, int tid) {
;     ...
;           for (int n = 0; n < 2; ++n) xi[m][n] = *reinterpret_cast<const float4*>(xin + (size_t)ACC_ROW * 2048 + ACC_COL);
; #pragma unroll
;         for (int m = 0; m < 4; ++m)
; #pragma unroll
;           for (int n = 0; n < 2; ++n) {
;             const f32x4 v = acc[ai][bj][m][n];
;             float4 r; r.x = xi[m][n].x + v[0]; r.y = xi[m][n].y + v[1]; r.z = xi[m][n].z + v[2]; r.w = xi[m][n].w + v[3];
;             *reinterpret_cast<float4*>(xout + (size_t)ACC_ROW * 2048 + ACC_COL) = r;
;           }
;         EPI_SCHED;
;       }
	v_pk_add_f32 v[126:127], v[126:127], v[180:181]
	v_pk_add_f32 v[128:129], v[128:129], v[182:183]
	global_store_dwordx4 v[140:141], v[126:129], off
	v_pk_add_f32 v[122:123], v[122:123], v[184:185]
	v_pk_add_f32 v[124:125], v[124:125], v[186:187]
	global_store_dwordx4 v[140:141], v[122:125], off offset:64
	v_pk_add_f32 v[118:119], v[118:119], v[188:189]
	v_pk_add_f32 v[120:121], v[120:121], v[190:191]
	global_store_dwordx4 v[138:139], v[118:121], off
	v_pk_add_f32 v[114:115], v[114:115], v[192:193]
	v_pk_add_f32 v[116:117], v[116:117], v[194:195]
	global_store_dwordx4 v[138:139], v[114:117], off offset:64
	v_pk_add_f32 v[110:111], v[110:111], v[196:197]
	v_pk_add_f32 v[112:113], v[112:113], v[198:199]
	global_store_dwordx4 v[136:137], v[110:113], off
	v_pk_add_f32 v[106:107], v[106:107], v[200:201]
	v_pk_add_f32 v[108:109], v[108:109], v[202:203]
	global_store_dwordx4 v[136:137], v[106:109], off offset:64
	v_pk_add_f32 v[102:103], v[102:103], v[204:205]
	v_pk_add_f32 v[104:105], v[104:105], v[206:207]
	global_store_dwordx4 v[134:135], v[102:105], off
	v_pk_add_f32 v[98:99], v[98:99], v[208:209]
	v_pk_add_f32 v[100:101], v[100:101], v[210:211]
	global_store_dwordx4 v[134:135], v[98:101], off offset:64
	global_load_dwordx4 v[180:183], v[140:141], off offset:512
	global_load_dwordx4 v[184:187], v[140:141], off offset:576
	global_load_dwordx4 v[188:191], v[138:139], off offset:512
	global_load_dwordx4 v[192:195], v[138:139], off offset:576
	global_load_dwordx4 v[196:199], v[136:137], off offset:512
	global_load_dwordx4 v[200:203], v[136:137], off offset:576
	global_load_dwordx4 v[204:207], v[134:135], off offset:512
	global_load_dwordx4 v[208:211], v[134:135], off offset:576
	s_waitcnt vmcnt(0)
	v_pk_add_f32 v[94:95], v[94:95], v[180:181]
	v_pk_add_f32 v[96:97], v[96:97], v[182:183]
	global_store_dwordx4 v[140:141], v[94:97], off offset:512
	v_pk_add_f32 v[90:91], v[90:91], v[184:185]
	v_pk_add_f32 v[92:93], v[92:93], v[186:187]
	global_store_dwordx4 v[140:141], v[90:93], off offset:576
	v_pk_add_f32 v[86:87], v[86:87], v[188:189]
	v_pk_add_f32 v[88:89], v[88:89], v[190:191]
	global_store_dwordx4 v[138:139], v[86:89], off offset:512
	v_pk_add_f32 v[82:83], v[82:83], v[192:193]
	v_pk_add_f32 v[84:85], v[84:85], v[194:195]
	global_store_dwordx4 v[138:139], v[82:85], off offset:576
	v_pk_add_f32 v[78:79], v[78:79], v[196:197]
	v_pk_add_f32 v[80:81], v[80:81], v[198:199]
	global_store_dwordx4 v[136:137], v[78:81], off offset:512
	v_pk_add_f32 v[74:75], v[74:75], v[200:201]
	v_pk_add_f32 v[76:77], v[76:77], v[202:203]
	global_store_dwordx4 v[136:137], v[74:77], off offset:576
	v_pk_add_f32 v[70:71], v[70:71], v[204:205]
	v_pk_add_f32 v[72:73], v[72:73], v[206:207]
	global_store_dwordx4 v[134:135], v[70:73], off offset:512
	v_pk_add_f32 v[66:67], v[66:67], v[208:209]
	v_pk_add_f32 v[68:69], v[68:69], v[210:211]
	global_store_dwordx4 v[134:135], v[66:69], off offset:576
	s_nop 1
	v_add_u32_e32 v66, 0x80, v130
	v_ashrrev_i32_e32 v67, 31, v66
	v_lshlrev_b64 v[66:67], 13, v[66:67]
	v_lshl_add_u64 v[66:67], s[72:73], 0, v[66:67]
	v_lshl_add_u64 v[72:73], v[66:67], 0, v[132:133]
	v_add_u32_e32 v66, 0x90, v130
	v_ashrrev_i32_e32 v67, 31, v66
	v_lshlrev_b64 v[66:67], 13, v[66:67]
	v_lshl_add_u64 v[66:67], s[72:73], 0, v[66:67]
	v_lshl_add_u64 v[70:71], v[66:67], 0, v[132:133]
	v_add_u32_e32 v66, 0xa0, v130
	v_ashrrev_i32_e32 v67, 31, v66
	v_lshlrev_b64 v[66:67], 13, v[66:67]
	v_lshl_add_u64 v[66:67], s[72:73], 0, v[66:67]
	v_lshl_add_u64 v[68:69], v[66:67], 0, v[132:133]
	v_add_u32_e32 v66, 0xb0, v130
	v_ashrrev_i32_e32 v67, 31, v66
	v_lshlrev_b64 v[66:67], 13, v[66:67]
	v_lshl_add_u64 v[66:67], s[72:73], 0, v[66:67]
	v_lshl_add_u64 v[66:67], v[66:67], 0, v[132:133]
	global_load_dwordx4 v[180:183], v[72:73], off
	global_load_dwordx4 v[184:187], v[72:73], off offset:64
	global_load_dwordx4 v[188:191], v[70:71], off
	global_load_dwordx4 v[192:195], v[70:71], off offset:64
	global_load_dwordx4 v[196:199], v[68:69], off
	global_load_dwordx4 v[200:203], v[68:69], off offset:64
	global_load_dwordx4 v[204:207], v[66:67], off
	global_load_dwordx4 v[208:211], v[66:67], off offset:64
	s_waitcnt vmcnt(0)
	v_pk_add_f32 v[62:63], v[62:63], v[180:181]
	v_pk_add_f32 v[64:65], v[64:65], v[182:183]
	global_store_dwordx4 v[72:73], v[62:65], off
	v_pk_add_f32 v[58:59], v[58:59], v[184:185]
	v_pk_add_f32 v[60:61], v[60:61], v[186:187]
	global_store_dwordx4 v[72:73], v[58:61], off offset:64
	v_pk_add_f32 v[54:55], v[54:55], v[188:189]
	v_pk_add_f32 v[56:57], v[56:57], v[190:191]
	global_store_dwordx4 v[70:71], v[54:57], off
	v_pk_add_f32 v[50:51], v[50:51], v[192:193]
	v_pk_add_f32 v[52:53], v[52:53], v[194:195]
	global_store_dwordx4 v[70:71], v[50:53], off offset:64
	v_pk_add_f32 v[46:47], v[46:47], v[196:197]
	v_pk_add_f32 v[48:49], v[48:49], v[198:199]
	global_store_dwordx4 v[68:69], v[46:49], off
	v_pk_add_f32 v[42:43], v[42:43], v[200:201]
	v_pk_add_f32 v[44:45], v[44:45], v[202:203]
	global_store_dwordx4 v[68:69], v[42:45], off offset:64
	v_pk_add_f32 v[38:39], v[38:39], v[204:205]
	v_pk_add_f32 v[40:41], v[40:41], v[206:207]
	global_store_dwordx4 v[66:67], v[38:41], off
	v_pk_add_f32 v[34:35], v[34:35], v[208:209]
	v_pk_add_f32 v[36:37], v[36:37], v[210:211]
	global_store_dwordx4 v[66:67], v[34:37], off offset:64
	global_load_dwordx4 v[180:183], v[72:73], off offset:512
	global_load_dwordx4 v[184:187], v[72:73], off offset:576
	global_load_dwordx4 v[188:191], v[70:71], off offset:512
	global_load_dwordx4 v[192:195], v[70:71], off offset:576
	global_load_dwordx4 v[196:199], v[68:69], off offset:512
	global_load_dwordx4 v[200:203], v[68:69], off offset:576
	global_load_dwordx4 v[204:207], v[66:67], off offset:512
	global_load_dwordx4 v[208:211], v[66:67], off offset:576
	s_waitcnt vmcnt(0)
	v_pk_add_f32 v[30:31], v[30:31], v[180:181]
	v_pk_add_f32 v[32:33], v[32:33], v[182:183]
	global_store_dwordx4 v[72:73], v[30:33], off offset:512
	v_pk_add_f32 v[26:27], v[26:27], v[184:185]
	v_pk_add_f32 v[28:29], v[28:29], v[186:187]
	global_store_dwordx4 v[72:73], v[26:29], off offset:576
	v_pk_add_f32 v[22:23], v[22:23], v[188:189]
	v_pk_add_f32 v[24:25], v[24:25], v[190:191]
	global_store_dwordx4 v[70:71], v[22:25], off offset:512
	v_pk_add_f32 v[18:19], v[18:19], v[192:193]
	v_pk_add_f32 v[20:21], v[20:21], v[194:195]
	global_store_dwordx4 v[70:71], v[18:21], off offset:576
	v_pk_add_f32 v[14:15], v[14:15], v[196:197]
	v_pk_add_f32 v[16:17], v[16:17], v[198:199]
	global_store_dwordx4 v[68:69], v[14:17], off offset:512
	v_pk_add_f32 v[10:11], v[10:11], v[200:201]
	v_pk_add_f32 v[12:13], v[12:13], v[202:203]
	global_store_dwordx4 v[68:69], v[10:13], off offset:576
	v_pk_add_f32 v[6:7], v[6:7], v[204:205]
	v_pk_add_f32 v[8:9], v[8:9], v[206:207]
	global_store_dwordx4 v[66:67], v[6:9], off offset:512
	v_pk_add_f32 v[2:3], v[2:3], v[208:209]
	v_pk_add_f32 v[4:5], v[4:5], v[210:211]
	global_store_dwordx4 v[66:67], v[2:5], off offset:576
	s_and_b64 vcc, exec, s[0:1]
	s_mov_b32 s8, s5
	s_mov_b32 s7, s6
	s_cbranch_vccz .LBB0_29
; #define WAIT_V(n) asm volatile("s_waitcnt vmcnt(" #n ")" ::: "memory")
; #define BAR __builtin_amdgcn_s_barrier()
; template <class EPI>
; DI void gemm_stream(const u16* __restrict__ A, const u16* __restrict__ Bt, const int K, const int nM, const int nN,
;                     const int bid, const int nb, const int tid, EPI epi) {
;     ...
;   WAIT_V(0);
;   if (wr == 0) BAR;
;   BAR;
	s_waitcnt vmcnt(0)
	s_movk_i32 s0, 0x100
	v_cmp_gt_u32_e32 vcc, s0, v239
	s_and_saveexec_b64 s[0:1], vcc
	s_cbranch_execz .LBB0_36
	s_barrier

; template <class EPI>
; DI void gemm_stream(const u16* __restrict__ A, const u16* __restrict__ Bt, const int K, const int nM, const int nN,
;                     const int bid, const int nb, const int tid, EPI epi) {
;     ...
;     for (int t = 0; t < nt; t += 2) {
;       const bool inside = (t + 2 < nt);
;       const int brs = inside ? brow : brow2, bcs = inside ? bcol : bcol2, t2 = inside ? t + 2 : 0;
.LBB0_46:
	v_or_b32_e32 v149, 0x10000, v146
	v_add_u32_e32 v154, 0x10400, v146
	ds_read_b128 v[150:153], v149
	ds_read_b128 v[154:157], v154
	v_add_u32_e32 v149, 0x10800, v146
	v_add_u32_e32 v162, 0x10c00, v146
	ds_read_b128 v[158:161], v149
	ds_read_b128 v[166:169], v162
	s_add_i32 s11, s10, -2
	s_cmp_lt_u32 s11, 30
	s_cselect_b32 s12, s9, s6
	s_cselect_b32 s13, s8, s5
	v_add_u32_e32 v162, 0xc000, v0
	v_add_u32_e32 v149, 0xfffc0000, v148
	v_readfirstlane_b32 s14, v162
	s_mov_b32 m0, s14
	ds_read_b128 v[170:173], v145
	ds_read_b128 v[174:177], v145 offset:1024
	ds_read_b128 v[180:183], v145 offset:2048
	ds_read_b128 v[184:187], v145 offset:3072
	ds_read_b128 v[188:191], v145 offset:4096
	ds_read_b128 v[192:195], v145 offset:5120
	ds_read_b128 v[196:199], v145 offset:6144
	ds_read_b128 v[200:203], v145 offset:7168
	global_load_lds_dwordx4 v149, s[80:81]
	s_waitcnt lgkmcnt(8)
	v_or_b32_e32 v149, 0x14000, v146
	v_add_u32_e32 v162, 0x14400, v146
	ds_read_b128 v[204:207], v149
	ds_read_b128 v[208:211], v162
	v_add_u32_e32 v149, 0x14800, v146
	v_add_u32_e32 v162, 0x14c00, v146
	ds_read_b128 v[212:215], v149
	ds_read_b128 v[216:219], v162
	v_add_u32_e32 v149, 0xe000, v0
	s_nop 0
	v_readfirstlane_b32 s14, v149
	s_mov_b32 m0, s14
	s_nop 0
	global_load_lds_dwordx4 v148, s[80:81]
	s_waitcnt vmcnt(8)
	s_waitcnt lgkmcnt(0)
	s_barrier
	v_mfma_f32_16x16x32_bf16 v[126:129], v[150:153], v[170:173], v[126:129]
	v_mfma_f32_16x16x32_bf16 v[118:121], v[158:161], v[170:173], v[118:121]
	v_mfma_f32_16x16x32_bf16 v[110:113], v[150:153], v[180:183], v[110:113]
	v_mfma_f32_16x16x32_bf16 v[102:105], v[158:161], v[180:183], v[102:105]
	v_mfma_f32_16x16x32_bf16 v[94:97], v[150:153], v[188:191], v[94:97]
	v_mfma_f32_16x16x32_bf16 v[86:89], v[158:161], v[188:191], v[86:89]
	v_mfma_f32_16x16x32_bf16 v[78:81], v[150:153], v[196:199], v[78:81]
	v_mfma_f32_16x16x32_bf16 v[70:73], v[158:161], v[196:199], v[70:73]
	v_mfma_f32_16x16x32_bf16 v[126:129], v[154:157], v[174:177], v[126:129]
	v_mfma_f32_16x16x32_bf16 v[118:121], v[166:169], v[174:177], v[118:121]
	v_mfma_f32_16x16x32_bf16 v[110:113], v[154:157], v[184:187], v[110:113]
	v_mfma_f32_16x16x32_bf16 v[102:105], v[166:169], v[184:187], v[102:105]
	v_mfma_f32_16x16x32_bf16 v[94:97], v[154:157], v[192:195], v[94:97]
	v_mfma_f32_16x16x32_bf16 v[86:89], v[166:169], v[192:195], v[86:89]
	v_mfma_f32_16x16x32_bf16 v[78:81], v[154:157], v[200:203], v[78:81]
	v_mfma_f32_16x16x32_bf16 v[70:73], v[166:169], v[200:203], v[70:73]
	v_mfma_f32_16x16x32_bf16 v[122:125], v[204:207], v[170:173], v[122:125]
	v_mfma_f32_16x16x32_bf16 v[114:117], v[212:215], v[170:173], v[114:117]
	v_mfma_f32_16x16x32_bf16 v[106:109], v[204:207], v[180:183], v[106:109]
	v_mfma_f32_16x16x32_bf16 v[98:101], v[212:215], v[180:183], v[98:101]
	v_mfma_f32_16x16x32_bf16 v[90:93], v[204:207], v[188:191], v[90:93]
	v_mfma_f32_16x16x32_bf16 v[82:85], v[212:215], v[188:191], v[82:85]
	v_mfma_f32_16x16x32_bf16 v[74:77], v[204:207], v[196:199], v[74:77]
	v_mfma_f32_16x16x32_bf16 v[66:69], v[212:215], v[196:199], v[66:69]
	v_mfma_f32_16x16x32_bf16 v[122:125], v[208:211], v[174:177], v[122:125]
	v_mfma_f32_16x16x32_bf16 v[114:117], v[216:219], v[174:177], v[114:117]
	v_mfma_f32_16x16x32_bf16 v[106:109], v[208:211], v[184:187], v[106:109]
	v_mfma_f32_16x16x32_bf16 v[98:101], v[216:219], v[184:187], v[98:101]
	v_mfma_f32_16x16x32_bf16 v[90:93], v[208:211], v[192:195], v[90:93]
	v_mfma_f32_16x16x32_bf16 v[82:85], v[216:219], v[192:195], v[82:85]
	v_mfma_f32_16x16x32_bf16 v[74:77], v[208:211], v[200:203], v[74:77]
	v_mfma_f32_16x16x32_bf16 v[66:69], v[216:219], v[200:203], v[66:69]
	s_barrier
	s_cselect_b32 s14, s10, 0
	s_lshl_b32 s12, s12, 11
	s_lshl_b32 s15, s14, 6
	s_or_b32 s16, s12, s15
	s_lshl_b32 s16, s16, 1
	v_readfirstlane_b32 s17, v132
	v_add_u32_e32 v149, s16, v130
	s_mov_b32 m0, s17
	s_nop 0
	global_load_lds_dwordx4 v149, s[82:83]
	v_add_u32_e32 v149, s16, v131
	v_readfirstlane_b32 s16, v133
	s_mov_b32 m0, s16
	s_nop 0
	global_load_lds_dwordx4 v149, s[82:83]
	s_lshl_b32 s16, s13, 11
	s_or_b32 s17, s16, s15
	s_lshl_b32 s17, s17, 1
	v_readfirstlane_b32 s18, v0
	v_add_u32_e32 v149, s17, v130
	s_mov_b32 m0, s18
	ds_read_b128 v[170:173], v145 offset:16384
	ds_read_b128 v[174:177], v145 offset:17408
	ds_read_b128 v[180:183], v145 offset:18432
	ds_read_b128 v[184:187], v145 offset:19456
	ds_read_b128 v[188:191], v145 offset:20480
	ds_read_b128 v[192:195], v145 offset:21504
	ds_read_b128 v[196:199], v145 offset:22528
	ds_read_b128 v[200:203], v145 offset:23552
	global_load_lds_dwordx4 v149, s[80:81]
	v_add_u32_e32 v149, s17, v131
	v_readfirstlane_b32 s17, v134
	s_mov_b32 m0, s17
	s_nop 0
	global_load_lds_dwordx4 v149, s[80:81]
	s_or_b32 s17, s12, 0x40000
	s_or_b32 s18, s17, s15
	s_lshl_b32 s18, s18, 1
	v_readfirstlane_b32 s19, v135
	v_add_u32_e32 v149, s18, v130
	s_mov_b32 m0, s19
	s_nop 0
	global_load_lds_dwordx4 v149, s[82:83]
	v_add_u32_e32 v149, s18, v131
	v_readfirstlane_b32 s18, v136
	s_mov_b32 m0, s18
	s_nop 0
	global_load_lds_dwordx4 v149, s[82:83]
	s_waitcnt vmcnt(8)
	s_waitcnt lgkmcnt(0)
	s_barrier
	v_mfma_f32_16x16x32_bf16 v[62:65], v[150:153], v[170:173], v[62:65]
	v_mfma_f32_16x16x32_bf16 v[54:57], v[158:161], v[170:173], v[54:57]
	v_mfma_f32_16x16x32_bf16 v[46:49], v[150:153], v[180:183], v[46:49]
	v_mfma_f32_16x16x32_bf16 v[38:41], v[158:161], v[180:183], v[38:41]
	v_mfma_f32_16x16x32_bf16 v[30:33], v[150:153], v[188:191], v[30:33]
	v_mfma_f32_16x16x32_bf16 v[22:25], v[158:161], v[188:191], v[22:25]
	v_mfma_f32_16x16x32_bf16 v[14:17], v[150:153], v[196:199], v[14:17]
	v_mfma_f32_16x16x32_bf16 v[6:9], v[158:161], v[196:199], v[6:9]
	v_mfma_f32_16x16x32_bf16 v[62:65], v[154:157], v[174:177], v[62:65]
	v_mfma_f32_16x16x32_bf16 v[54:57], v[166:169], v[174:177], v[54:57]
	v_mfma_f32_16x16x32_bf16 v[46:49], v[154:157], v[184:187], v[46:49]
	v_mfma_f32_16x16x32_bf16 v[38:41], v[166:169], v[184:187], v[38:41]
	v_mfma_f32_16x16x32_bf16 v[30:33], v[154:157], v[192:195], v[30:33]
	v_mfma_f32_16x16x32_bf16 v[22:25], v[166:169], v[192:195], v[22:25]
	v_mfma_f32_16x16x32_bf16 v[14:17], v[154:157], v[200:203], v[14:17]
	v_mfma_f32_16x16x32_bf16 v[6:9], v[166:169], v[200:203], v[6:9]
	v_mfma_f32_16x16x32_bf16 v[58:61], v[204:207], v[170:173], v[58:61]
	v_mfma_f32_16x16x32_bf16 v[50:53], v[212:215], v[170:173], v[50:53]
	v_mfma_f32_16x16x32_bf16 v[42:45], v[204:207], v[180:183], v[42:45]
	v_mfma_f32_16x16x32_bf16 v[34:37], v[212:215], v[180:183], v[34:37]
	v_mfma_f32_16x16x32_bf16 v[26:29], v[204:207], v[188:191], v[26:29]
	v_mfma_f32_16x16x32_bf16 v[18:21], v[212:215], v[188:191], v[18:21]
	v_mfma_f32_16x16x32_bf16 v[10:13], v[204:207], v[196:199], v[10:13]
	v_mfma_f32_16x16x32_bf16 v[2:5], v[212:215], v[196:199], v[2:5]
	v_mfma_f32_16x16x32_bf16 v[58:61], v[208:211], v[174:177], v[58:61]
	v_mfma_f32_16x16x32_bf16 v[50:53], v[216:219], v[174:177], v[50:53]
	v_mfma_f32_16x16x32_bf16 v[42:45], v[208:211], v[184:187], v[42:45]
	v_mfma_f32_16x16x32_bf16 v[34:37], v[216:219], v[184:187], v[34:37]
	v_mfma_f32_16x16x32_bf16 v[26:29], v[208:211], v[192:195], v[26:29]
	v_mfma_f32_16x16x32_bf16 v[18:21], v[216:219], v[192:195], v[18:21]
	v_mfma_f32_16x16x32_bf16 v[10:13], v[208:211], v[200:203], v[10:13]
	v_mfma_f32_16x16x32_bf16 v[2:5], v[216:219], v[200:203], v[2:5]
	s_barrier
	v_or_b32_e32 v149, 0x18000, v146
	v_add_u32_e32 v154, 0x18400, v146
	ds_read_b128 v[150:153], v149
	ds_read_b128 v[154:157], v154
	v_add_u32_e32 v149, 0x18800, v146
	v_add_u32_e32 v162, 0x18c00, v146
	ds_read_b128 v[158:161], v149
	ds_read_b128 v[166:169], v162
	s_lshl_b32 s13, s13, 12
	s_lshl_b32 s14, s14, 7
	s_add_i32 s13, s14, s13
	s_add_i32 s13, s13, 0x80000
	v_readfirstlane_b32 s14, v137
	v_add_u32_e32 v149, s13, v130
	s_mov_b32 m0, s14
	ds_read_b128 v[170:173], v145 offset:32768
	ds_read_b128 v[174:177], v145 offset:33792
	ds_read_b128 v[180:183], v145 offset:34816
	ds_read_b128 v[184:187], v145 offset:35840
	ds_read_b128 v[188:191], v145 offset:36864
	ds_read_b128 v[192:195], v145 offset:37888
	ds_read_b128 v[196:199], v145 offset:38912
	ds_read_b128 v[200:203], v145 offset:39936
	global_load_lds_dwordx4 v149, s[80:81]
	s_waitcnt lgkmcnt(8)
	v_or_b32_e32 v149, 0x1c000, v146
	v_add_u32_e32 v162, 0x1c400, v146
	ds_read_b128 v[204:207], v149
	ds_read_b128 v[208:211], v162
	v_add_u32_e32 v149, 0x1c800, v146
	v_add_u32_e32 v162, 0x1cc00, v146
	ds_read_b128 v[212:215], v149
	ds_read_b128 v[216:219], v162
	v_add_u32_e32 v149, s13, v131
	v_readfirstlane_b32 s13, v138
	s_mov_b32 m0, s13
	s_nop 0
	global_load_lds_dwordx4 v149, s[80:81]
	s_waitcnt vmcnt(8)
	s_waitcnt lgkmcnt(0)
	s_barrier
	v_mfma_f32_16x16x32_bf16 v[126:129], v[150:153], v[170:173], v[126:129]
	v_mfma_f32_16x16x32_bf16 v[118:121], v[158:161], v[170:173], v[118:121]
	v_mfma_f32_16x16x32_bf16 v[110:113], v[150:153], v[180:183], v[110:113]
	v_mfma_f32_16x16x32_bf16 v[102:105], v[158:161], v[180:183], v[102:105]
	v_mfma_f32_16x16x32_bf16 v[94:97], v[150:153], v[188:191], v[94:97]
	v_mfma_f32_16x16x32_bf16 v[86:89], v[158:161], v[188:191], v[86:89]
	v_mfma_f32_16x16x32_bf16 v[78:81], v[150:153], v[196:199], v[78:81]
	v_mfma_f32_16x16x32_bf16 v[70:73], v[158:161], v[196:199], v[70:73]
	v_mfma_f32_16x16x32_bf16 v[126:129], v[154:157], v[174:177], v[126:129]
	v_mfma_f32_16x16x32_bf16 v[118:121], v[166:169], v[174:177], v[118:121]
	v_mfma_f32_16x16x32_bf16 v[110:113], v[154:157], v[184:187], v[110:113]
	v_mfma_f32_16x16x32_bf16 v[102:105], v[166:169], v[184:187], v[102:105]
	v_mfma_f32_16x16x32_bf16 v[94:97], v[154:157], v[192:195], v[94:97]
	v_mfma_f32_16x16x32_bf16 v[86:89], v[166:169], v[192:195], v[86:89]
	v_mfma_f32_16x16x32_bf16 v[78:81], v[154:157], v[200:203], v[78:81]
	v_mfma_f32_16x16x32_bf16 v[70:73], v[166:169], v[200:203], v[70:73]
	v_mfma_f32_16x16x32_bf16 v[122:125], v[204:207], v[170:173], v[122:125]
	v_mfma_f32_16x16x32_bf16 v[114:117], v[212:215], v[170:173], v[114:117]
	v_mfma_f32_16x16x32_bf16 v[106:109], v[204:207], v[180:183], v[106:109]
	v_mfma_f32_16x16x32_bf16 v[98:101], v[212:215], v[180:183], v[98:101]
	v_mfma_f32_16x16x32_bf16 v[90:93], v[204:207], v[188:191], v[90:93]
	v_mfma_f32_16x16x32_bf16 v[82:85], v[212:215], v[188:191], v[82:85]
	v_mfma_f32_16x16x32_bf16 v[74:77], v[204:207], v[196:199], v[74:77]
	v_mfma_f32_16x16x32_bf16 v[66:69], v[212:215], v[196:199], v[66:69]
	v_mfma_f32_16x16x32_bf16 v[122:125], v[208:211], v[174:177], v[122:125]
	v_mfma_f32_16x16x32_bf16 v[114:117], v[216:219], v[174:177], v[114:117]
	v_mfma_f32_16x16x32_bf16 v[106:109], v[208:211], v[184:187], v[106:109]
	v_mfma_f32_16x16x32_bf16 v[98:101], v[216:219], v[184:187], v[98:101]
	v_mfma_f32_16x16x32_bf16 v[90:93], v[208:211], v[192:195], v[90:93]
	v_mfma_f32_16x16x32_bf16 v[82:85], v[216:219], v[192:195], v[82:85]
	v_mfma_f32_16x16x32_bf16 v[74:77], v[208:211], v[200:203], v[74:77]
	v_mfma_f32_16x16x32_bf16 v[66:69], v[216:219], v[200:203], v[66:69]
	s_barrier
; DI float sigmoidf_(float v) { return __builtin_amdgcn_rcpf(1.f + __expf(-v)); }
; DI void gemm_gateup(const Params& p, int bid, int nb, int tid) {
;     ...
;     _Pragma("unroll") for (int ai = 0; ai < 2; ++ai) _Pragma("unroll") for (int m = 0; m < 4; ++m) _Pragma("unroll") for (int n = 0; n < 2; ++n) {
;       const int col = pn * 128 + wc * 32 + n * 16 + fq * 4;
;       const int row = brow + ai * HALF + wr * 64 + m * 16 + fr;
;       const f32x4 g = acc[ai][0][m][n], uu = acc[ai][1][m][n];
;       uint2 w;
;       w.x = pk2(g[0] * sigmoidf_(g[0]) * uu[0], g[1] * sigmoidf_(g[1]) * uu[1]);
;       w.y = pk2(g[2] * sigmoidf_(g[2]) * uu[2], g[3] * sigmoidf_(g[3]) * uu[3]);
;       *reinterpret_cast<uint2*>(C + (size_t)row * DFF + col) = w;
	s_or_b32 s13, s15, 64
	s_or_b32 s12, s13, s12
	s_lshl_b32 s12, s12, 1
	v_readfirstlane_b32 s14, v139
	v_add_u32_e32 v149, s12, v130
	s_mov_b32 m0, s14
	s_nop 0
	global_load_lds_dwordx4 v149, s[82:83]
	v_add_u32_e32 v149, s12, v131
	v_readfirstlane_b32 s12, v140
	s_mov_b32 m0, s12
	s_nop 0
	global_load_lds_dwordx4 v149, s[82:83]
	s_or_b32 s12, s13, s16
	s_lshl_b32 s12, s12, 1
	v_readfirstlane_b32 s14, v141
	v_add_u32_e32 v149, s12, v130
	s_mov_b32 m0, s14
	ds_read_b128 v[170:173], v145 offset:49152
	ds_read_b128 v[174:177], v145 offset:50176
	ds_read_b128 v[180:183], v145 offset:51200
	ds_read_b128 v[184:187], v145 offset:52224
	ds_read_b128 v[188:191], v145 offset:53248
	ds_read_b128 v[192:195], v145 offset:54272
	ds_read_b128 v[196:199], v145 offset:55296
	ds_read_b128 v[200:203], v145 offset:56320
	global_load_lds_dwordx4 v149, s[80:81]
	v_add_u32_e32 v149, s12, v131
	v_readfirstlane_b32 s12, v142
	s_mov_b32 m0, s12
	s_nop 0
	global_load_lds_dwordx4 v149, s[80:81]
	s_or_b32 s12, s17, s13
	s_lshl_b32 s12, s12, 1
	v_readfirstlane_b32 s13, v143
	v_add_u32_e32 v149, s12, v130
	s_mov_b32 m0, s13
	s_nop 0
	global_load_lds_dwordx4 v149, s[82:83]
	v_add_u32_e32 v149, s12, v131
	v_readfirstlane_b32 s12, v144
	s_mov_b32 m0, s12
	s_nop 0
	global_load_lds_dwordx4 v149, s[82:83]
	s_waitcnt vmcnt(8)
	s_waitcnt lgkmcnt(0)
	s_barrier
	v_mfma_f32_16x16x32_bf16 v[62:65], v[150:153], v[170:173], v[62:65]
	v_mfma_f32_16x16x32_bf16 v[54:57], v[158:161], v[170:173], v[54:57]
	v_mfma_f32_16x16x32_bf16 v[46:49], v[150:153], v[180:183], v[46:49]
	v_mfma_f32_16x16x32_bf16 v[38:41], v[158:161], v[180:183], v[38:41]
	v_mfma_f32_16x16x32_bf16 v[30:33], v[150:153], v[188:191], v[30:33]
	v_mfma_f32_16x16x32_bf16 v[22:25], v[158:161], v[188:191], v[22:25]
	v_mfma_f32_16x16x32_bf16 v[14:17], v[150:153], v[196:199], v[14:17]
	v_mfma_f32_16x16x32_bf16 v[6:9], v[158:161], v[196:199], v[6:9]
	v_mfma_f32_16x16x32_bf16 v[62:65], v[154:157], v[174:177], v[62:65]
	v_mfma_f32_16x16x32_bf16 v[54:57], v[166:169], v[174:177], v[54:57]
	v_mfma_f32_16x16x32_bf16 v[46:49], v[154:157], v[184:187], v[46:49]
	v_mfma_f32_16x16x32_bf16 v[38:41], v[166:169], v[184:187], v[38:41]
	v_mfma_f32_16x16x32_bf16 v[30:33], v[154:157], v[192:195], v[30:33]
	v_mfma_f32_16x16x32_bf16 v[22:25], v[166:169], v[192:195], v[22:25]
	v_mfma_f32_16x16x32_bf16 v[14:17], v[154:157], v[200:203], v[14:17]
	v_mfma_f32_16x16x32_bf16 v[6:9], v[166:169], v[200:203], v[6:9]
	v_mfma_f32_16x16x32_bf16 v[58:61], v[204:207], v[170:173], v[58:61]
	v_mfma_f32_16x16x32_bf16 v[50:53], v[212:215], v[170:173], v[50:53]
	v_mfma_f32_16x16x32_bf16 v[42:45], v[204:207], v[180:183], v[42:45]
	v_mfma_f32_16x16x32_bf16 v[34:37], v[212:215], v[180:183], v[34:37]
	v_mfma_f32_16x16x32_bf16 v[26:29], v[204:207], v[188:191], v[26:29]
	v_mfma_f32_16x16x32_bf16 v[18:21], v[212:215], v[188:191], v[18:21]
	v_mfma_f32_16x16x32_bf16 v[10:13], v[204:207], v[196:199], v[10:13]
	v_mfma_f32_16x16x32_bf16 v[2:5], v[212:215], v[196:199], v[2:5]
	v_mfma_f32_16x16x32_bf16 v[58:61], v[208:211], v[174:177], v[58:61]
	v_mfma_f32_16x16x32_bf16 v[50:53], v[216:219], v[174:177], v[50:53]
	v_mfma_f32_16x16x32_bf16 v[42:45], v[208:211], v[184:187], v[42:45]
	v_mfma_f32_16x16x32_bf16 v[34:37], v[216:219], v[184:187], v[34:37]
	v_mfma_f32_16x16x32_bf16 v[26:29], v[208:211], v[192:195], v[26:29]
	v_mfma_f32_16x16x32_bf16 v[18:21], v[216:219], v[192:195], v[18:21]
	v_mfma_f32_16x16x32_bf16 v[10:13], v[208:211], v[200:203], v[10:13]
	v_mfma_f32_16x16x32_bf16 v[2:5], v[216:219], v[200:203], v[2:5]
	s_add_i32 s10, s10, 2
	s_cmp_gt_u32 s11, 29
	v_add_u32_e32 v148, 0x100, v148
	s_barrier
	s_cbranch_scc0 .LBB0_46
	v_mov_b32_e32 v148, v239
	s_lshl_b32 s7, s7, 7
	v_lshrrev_b32_e32 v149, 1, v148
	v_lshrrev_b32_e32 v150, 2, v148
	v_and_b32_e32 v149, 0x60, v149
	v_and_b32_e32 v150, 12, v150
	v_or3_b32 v150, v149, s7, v150
	v_ashrrev_i32_e32 v149, 2, v148
	v_and_b32_e32 v149, 0xffffffc0, v149
	v_and_or_b32 v148, v148, 15, s8
	v_add_u32_e32 v148, v148, v149
	v_mul_f32_e32 v149, 0xbfb8aa3b, v126
	v_exp_f32_e32 v149, v149
	s_movk_i32 s7, 0x2c00
	v_ashrrev_i32_e32 v151, 31, v150
	v_add_f32_e32 v149, 1.0, v149
	v_rcp_f32_e32 v152, v149
	v_mul_f32_e32 v149, 0xbfb8aa3b, v127
	v_exp_f32_e32 v149, v149
	s_nop 0
	v_add_f32_e32 v149, 1.0, v149
	v_rcp_f32_e32 v153, v149
	s_nop 0
	v_pk_mul_f32 v[126:127], v[126:127], v[152:153]
	s_nop 0
	v_pk_mul_f32 v[122:123], v[126:127], v[122:123]
	s_nop 0
	v_cvt_pk_bf16_f32 v126, v122, v123
	v_mul_f32_e32 v122, 0xbfb8aa3b, v128
	v_mul_f32_e32 v123, 0xbfb8aa3b, v129
	v_exp_f32_e32 v122, v122
	v_exp_f32_e32 v123, v123
	v_add_f32_e32 v122, 1.0, v122
	v_add_f32_e32 v123, 1.0, v123
	v_rcp_f32_e32 v122, v122
	v_rcp_f32_e32 v123, v123
	s_nop 0
	v_pk_mul_f32 v[122:123], v[128:129], v[122:123]
	s_nop 0
	v_pk_mul_f32 v[122:123], v[122:123], v[124:125]
	v_lshlrev_b64 v[124:125], 1, v[150:151]
	v_cvt_pk_bf16_f32 v127, v122, v123
	v_mov_b64_e32 v[122:123], s[76:77]
	v_mad_i64_i32 v[128:129], s[8:9], v148, s7, v[122:123]
	v_lshl_add_u64 v[128:129], v[128:129], 0, v[124:125]
	global_store_dwordx2 v[128:129], v[126:127], off
	v_mul_f32_e32 v126, 0xbfb8aa3b, v118
	v_mul_f32_e32 v127, 0xbfb8aa3b, v119
	v_exp_f32_e32 v126, v126
	v_exp_f32_e32 v127, v127
	v_add_f32_e32 v126, 1.0, v126
	v_add_f32_e32 v127, 1.0, v127
	v_rcp_f32_e32 v126, v126
	v_rcp_f32_e32 v127, v127
	s_nop 0
	v_pk_mul_f32 v[118:119], v[118:119], v[126:127]
	s_nop 0
	v_pk_mul_f32 v[114:115], v[118:119], v[114:115]
	s_nop 0
	v_cvt_pk_bf16_f32 v114, v114, v115
	v_mul_f32_e32 v115, 0xbfb8aa3b, v120
	v_exp_f32_e32 v115, v115
	s_nop 0
	v_add_f32_e32 v115, 1.0, v115
	v_rcp_f32_e32 v118, v115
; DI float sigmoidf_(float v) { return __builtin_amdgcn_rcpf(1.f + __expf(-v)); }
; #define EPI_SCHED __builtin_amdgcn_sched_barrier(0)
; DI void gemm_gateup(const Params& p, int bid, int nb, int tid) {
;     ...
;     _Pragma("unroll") for (int ai = 0; ai < 2; ++ai) _Pragma("unroll") for (int m = 0; m < 4; ++m) _Pragma("unroll") for (int n = 0; n < 2; ++n) {
;       const int col = pn * 128 + wc * 32 + n * 16 + fq * 4;
;       const int row = brow + ai * HALF + wr * 64 + m * 16 + fr;
;       const f32x4 g = acc[ai][0][m][n], uu = acc[ai][1][m][n];
;       uint2 w;
;       w.x = pk2(g[0] * sigmoidf_(g[0]) * uu[0], g[1] * sigmoidf_(g[1]) * uu[1]);
;       w.y = pk2(g[2] * sigmoidf_(g[2]) * uu[2], g[3] * sigmoidf_(g[3]) * uu[3]);
;       *reinterpret_cast<uint2*>(C + (size_t)row * DFF + col) = w;
;       EPI_SCHED;
;     }
	v_mul_f32_e32 v115, 0xbfb8aa3b, v121
	v_exp_f32_e32 v115, v115
	s_nop 0
	v_add_f32_e32 v115, 1.0, v115
	v_rcp_f32_e32 v119, v115
	s_nop 0
	v_pk_mul_f32 v[118:119], v[120:121], v[118:119]
	s_nop 0
	v_pk_mul_f32 v[116:117], v[118:119], v[116:117]
	s_nop 0
	v_cvt_pk_bf16_f32 v115, v116, v117
	global_store_dwordx2 v[128:129], v[114:115], off offset:32
	v_mul_f32_e32 v114, 0xbfb8aa3b, v110
	v_mul_f32_e32 v115, 0xbfb8aa3b, v111
	v_exp_f32_e32 v114, v114
	v_exp_f32_e32 v115, v115
	v_or_b32_e32 v116, 16, v148
	v_add_f32_e32 v114, 1.0, v114
	v_add_f32_e32 v115, 1.0, v115
	v_rcp_f32_e32 v114, v114
	v_rcp_f32_e32 v115, v115
	s_nop 0
	v_pk_mul_f32 v[110:111], v[110:111], v[114:115]
	s_nop 0
	v_pk_mul_f32 v[106:107], v[110:111], v[106:107]
	s_nop 0
	v_cvt_pk_bf16_f32 v106, v106, v107
	v_mul_f32_e32 v107, 0xbfb8aa3b, v112
	v_exp_f32_e32 v107, v107
	s_nop 0
	v_add_f32_e32 v107, 1.0, v107
	v_rcp_f32_e32 v110, v107
	v_mul_f32_e32 v107, 0xbfb8aa3b, v113
	v_exp_f32_e32 v107, v107
	s_nop 0
	v_add_f32_e32 v107, 1.0, v107
	v_rcp_f32_e32 v111, v107
	s_nop 0
	v_pk_mul_f32 v[110:111], v[112:113], v[110:111]
	s_nop 0
	v_pk_mul_f32 v[108:109], v[110:111], v[108:109]
	s_nop 0
	v_cvt_pk_bf16_f32 v107, v108, v109
	v_mad_i64_i32 v[108:109], s[8:9], v116, s7, v[122:123]
	v_lshl_add_u64 v[108:109], v[108:109], 0, v[124:125]
	global_store_dwordx2 v[108:109], v[106:107], off
	v_mul_f32_e32 v106, 0xbfb8aa3b, v102
	v_mul_f32_e32 v107, 0xbfb8aa3b, v103
	v_exp_f32_e32 v106, v106
	v_exp_f32_e32 v107, v107
	v_add_f32_e32 v106, 1.0, v106
	v_add_f32_e32 v107, 1.0, v107
	v_rcp_f32_e32 v106, v106
	v_rcp_f32_e32 v107, v107
	s_nop 0
	v_pk_mul_f32 v[102:103], v[102:103], v[106:107]
	s_nop 0
	v_pk_mul_f32 v[98:99], v[102:103], v[98:99]
	s_nop 0
	v_cvt_pk_bf16_f32 v98, v98, v99
	v_mul_f32_e32 v99, 0xbfb8aa3b, v104
	v_exp_f32_e32 v99, v99
	s_nop 0
	v_add_f32_e32 v99, 1.0, v99
	v_rcp_f32_e32 v102, v99
	v_mul_f32_e32 v99, 0xbfb8aa3b, v105
	v_exp_f32_e32 v99, v99
	s_nop 0
	v_add_f32_e32 v99, 1.0, v99
	v_rcp_f32_e32 v103, v99
	s_nop 0
	v_pk_mul_f32 v[102:103], v[104:105], v[102:103]
	s_nop 0
	v_pk_mul_f32 v[100:101], v[102:103], v[100:101]
	s_nop 0
	v_cvt_pk_bf16_f32 v99, v100, v101
	global_store_dwordx2 v[108:109], v[98:99], off offset:32
	v_mul_f32_e32 v98, 0xbfb8aa3b, v94
	v_mul_f32_e32 v99, 0xbfb8aa3b, v95
	v_exp_f32_e32 v98, v98
	v_exp_f32_e32 v99, v99
	v_or_b32_e32 v100, 32, v148
	v_add_f32_e32 v98, 1.0, v98
	v_add_f32_e32 v99, 1.0, v99
	v_rcp_f32_e32 v98, v98
	v_rcp_f32_e32 v99, v99
	s_nop 0
	v_pk_mul_f32 v[94:95], v[94:95], v[98:99]
	s_nop 0
	v_pk_mul_f32 v[90:91], v[94:95], v[90:91]
	s_nop 0
	v_cvt_pk_bf16_f32 v90, v90, v91
	v_mul_f32_e32 v91, 0xbfb8aa3b, v96
	v_exp_f32_e32 v91, v91
	s_nop 0
	v_add_f32_e32 v91, 1.0, v91
	v_rcp_f32_e32 v94, v91
	v_mul_f32_e32 v91, 0xbfb8aa3b, v97
	v_exp_f32_e32 v91, v91
	s_nop 0
	v_add_f32_e32 v91, 1.0, v91
	v_rcp_f32_e32 v95, v91
	s_nop 0
	v_pk_mul_f32 v[94:95], v[96:97], v[94:95]
	s_nop 0
	v_pk_mul_f32 v[92:93], v[94:95], v[92:93]
	s_nop 0
	v_cvt_pk_bf16_f32 v91, v92, v93
	v_mad_i64_i32 v[92:93], s[8:9], v100, s7, v[122:123]
	v_lshl_add_u64 v[92:93], v[92:93], 0, v[124:125]
	global_store_dwordx2 v[92:93], v[90:91], off
	v_mul_f32_e32 v90, 0xbfb8aa3b, v86
	v_mul_f32_e32 v91, 0xbfb8aa3b, v87
	v_exp_f32_e32 v90, v90
	v_exp_f32_e32 v91, v91
	v_add_f32_e32 v90, 1.0, v90
	v_add_f32_e32 v91, 1.0, v91
	v_rcp_f32_e32 v90, v90
	v_rcp_f32_e32 v91, v91
	s_nop 0
	v_pk_mul_f32 v[86:87], v[86:87], v[90:91]
	s_nop 0
	v_pk_mul_f32 v[82:83], v[86:87], v[82:83]
	s_nop 0
	v_cvt_pk_bf16_f32 v82, v82, v83
	v_mul_f32_e32 v83, 0xbfb8aa3b, v88
	v_exp_f32_e32 v83, v83
	s_nop 0
	v_add_f32_e32 v83, 1.0, v83
	v_rcp_f32_e32 v86, v83
	v_mul_f32_e32 v83, 0xbfb8aa3b, v89
	v_exp_f32_e32 v83, v83
	s_nop 0
	v_add_f32_e32 v83, 1.0, v83
	v_rcp_f32_e32 v87, v83
	s_nop 0
	v_pk_mul_f32 v[86:87], v[88:89], v[86:87]
	s_nop 0
	v_pk_mul_f32 v[84:85], v[86:87], v[84:85]
	s_nop 0
	v_cvt_pk_bf16_f32 v83, v84, v85
	global_store_dwordx2 v[92:93], v[82:83], off offset:32
	v_mul_f32_e32 v82, 0xbfb8aa3b, v78
	v_mul_f32_e32 v83, 0xbfb8aa3b, v79
	v_exp_f32_e32 v82, v82
	v_exp_f32_e32 v83, v83
	v_or_b32_e32 v84, 48, v148
	v_add_f32_e32 v82, 1.0, v82
	v_add_f32_e32 v83, 1.0, v83
	v_rcp_f32_e32 v82, v82
	v_rcp_f32_e32 v83, v83
	s_nop 0
	v_pk_mul_f32 v[78:79], v[78:79], v[82:83]
	s_nop 0
	v_pk_mul_f32 v[74:75], v[78:79], v[74:75]
	s_nop 0
	v_cvt_pk_bf16_f32 v74, v74, v75
	v_mul_f32_e32 v75, 0xbfb8aa3b, v80
	v_exp_f32_e32 v75, v75
	s_nop 0
	v_add_f32_e32 v75, 1.0, v75
	v_rcp_f32_e32 v78, v75
	v_mul_f32_e32 v75, 0xbfb8aa3b, v81
	v_exp_f32_e32 v75, v75
	s_nop 0
	v_add_f32_e32 v75, 1.0, v75
	v_rcp_f32_e32 v79, v75
	s_nop 0
	v_pk_mul_f32 v[78:79], v[80:81], v[78:79]
	s_nop 0
	v_pk_mul_f32 v[76:77], v[78:79], v[76:77]
	s_nop 0
	v_cvt_pk_bf16_f32 v75, v76, v77
	v_mad_i64_i32 v[76:77], s[8:9], v84, s7, v[122:123]
	v_lshl_add_u64 v[76:77], v[76:77], 0, v[124:125]
	global_store_dwordx2 v[76:77], v[74:75], off
	v_mul_f32_e32 v74, 0xbfb8aa3b, v70
	v_mul_f32_e32 v75, 0xbfb8aa3b, v71
	v_exp_f32_e32 v74, v74
	v_exp_f32_e32 v75, v75
	v_add_f32_e32 v74, 1.0, v74
	v_add_f32_e32 v75, 1.0, v75
	v_rcp_f32_e32 v74, v74
	v_rcp_f32_e32 v75, v75
	s_nop 0
	v_pk_mul_f32 v[70:71], v[70:71], v[74:75]
	s_nop 0
	v_pk_mul_f32 v[66:67], v[70:71], v[66:67]
	s_nop 0
	v_cvt_pk_bf16_f32 v66, v66, v67
	v_mul_f32_e32 v67, 0xbfb8aa3b, v72
	v_exp_f32_e32 v67, v67
	s_nop 0
	v_add_f32_e32 v67, 1.0, v67
	v_rcp_f32_e32 v70, v67
	v_mul_f32_e32 v67, 0xbfb8aa3b, v73
	v_exp_f32_e32 v67, v67
	s_nop 0
	v_add_f32_e32 v67, 1.0, v67
	v_rcp_f32_e32 v71, v67
	s_nop 0
	v_pk_mul_f32 v[70:71], v[72:73], v[70:71]
	s_nop 0
	v_pk_mul_f32 v[68:69], v[70:71], v[68:69]
; DI float sigmoidf_(float v) { return __builtin_amdgcn_rcpf(1.f + __expf(-v)); }
; #define EPI_SCHED __builtin_amdgcn_sched_barrier(0)
; DI void gemm_gateup(const Params& p, int bid, int nb, int tid) {
;     ...
;     _Pragma("unroll") for (int ai = 0; ai < 2; ++ai) _Pragma("unroll") for (int m = 0; m < 4; ++m) _Pragma("unroll") for (int n = 0; n < 2; ++n) {
;       const int col = pn * 128 + wc * 32 + n * 16 + fq * 4;
;       const int row = brow + ai * HALF + wr * 64 + m * 16 + fr;
;       const f32x4 g = acc[ai][0][m][n], uu = acc[ai][1][m][n];
;       uint2 w;
;       w.x = pk2(g[0] * sigmoidf_(g[0]) * uu[0], g[1] * sigmoidf_(g[1]) * uu[1]);
;       w.y = pk2(g[2] * sigmoidf_(g[2]) * uu[2], g[3] * sigmoidf_(g[3]) * uu[3]);
;       *reinterpret_cast<uint2*>(C + (size_t)row * DFF + col) = w;
;       EPI_SCHED;
;     }
	s_nop 0
	v_cvt_pk_bf16_f32 v67, v68, v69
	global_store_dwordx2 v[76:77], v[66:67], off offset:32
	v_mul_f32_e32 v66, 0xbfb8aa3b, v62
	v_mul_f32_e32 v67, 0xbfb8aa3b, v63
	v_exp_f32_e32 v66, v66
	v_exp_f32_e32 v67, v67
	v_add_u32_e32 v68, 0x80, v148
	v_add_f32_e32 v66, 1.0, v66
	v_add_f32_e32 v67, 1.0, v67
	v_rcp_f32_e32 v66, v66
	v_rcp_f32_e32 v67, v67
	s_nop 0
	v_pk_mul_f32 v[62:63], v[62:63], v[66:67]
	s_nop 0
	v_pk_mul_f32 v[58:59], v[62:63], v[58:59]
	s_nop 0
	v_cvt_pk_bf16_f32 v58, v58, v59
	v_mul_f32_e32 v59, 0xbfb8aa3b, v64
	v_exp_f32_e32 v59, v59
	s_nop 0
	v_add_f32_e32 v59, 1.0, v59
	v_rcp_f32_e32 v62, v59
	v_mul_f32_e32 v59, 0xbfb8aa3b, v65
	v_exp_f32_e32 v59, v59
	s_nop 0
	v_add_f32_e32 v59, 1.0, v59
	v_rcp_f32_e32 v63, v59
	s_nop 0
	v_pk_mul_f32 v[62:63], v[64:65], v[62:63]
	s_nop 0
	v_pk_mul_f32 v[60:61], v[62:63], v[60:61]
	s_nop 0
	v_cvt_pk_bf16_f32 v59, v60, v61
	v_mad_i64_i32 v[60:61], s[8:9], v68, s7, v[122:123]
	v_lshl_add_u64 v[60:61], v[60:61], 0, v[124:125]
	global_store_dwordx2 v[60:61], v[58:59], off
	v_mul_f32_e32 v58, 0xbfb8aa3b, v54
	v_mul_f32_e32 v59, 0xbfb8aa3b, v55
	v_exp_f32_e32 v58, v58
	v_exp_f32_e32 v59, v59
	v_add_f32_e32 v58, 1.0, v58
	v_add_f32_e32 v59, 1.0, v59
	v_rcp_f32_e32 v58, v58
	v_rcp_f32_e32 v59, v59
	s_nop 0
	v_pk_mul_f32 v[54:55], v[54:55], v[58:59]
	s_nop 0
	v_pk_mul_f32 v[50:51], v[54:55], v[50:51]
	s_nop 0
	v_cvt_pk_bf16_f32 v50, v50, v51
	v_mul_f32_e32 v51, 0xbfb8aa3b, v56
	v_exp_f32_e32 v51, v51
	s_nop 0
	v_add_f32_e32 v51, 1.0, v51
	v_rcp_f32_e32 v54, v51
	v_mul_f32_e32 v51, 0xbfb8aa3b, v57
	v_exp_f32_e32 v51, v51
	s_nop 0
	v_add_f32_e32 v51, 1.0, v51
	v_rcp_f32_e32 v55, v51
	s_nop 0
	v_pk_mul_f32 v[54:55], v[56:57], v[54:55]
	s_nop 0
	v_pk_mul_f32 v[52:53], v[54:55], v[52:53]
	s_nop 0
	v_cvt_pk_bf16_f32 v51, v52, v53
	global_store_dwordx2 v[60:61], v[50:51], off offset:32
	v_mul_f32_e32 v50, 0xbfb8aa3b, v46
	v_mul_f32_e32 v51, 0xbfb8aa3b, v47
	v_exp_f32_e32 v50, v50
	v_exp_f32_e32 v51, v51
	v_add_u32_e32 v52, 0x90, v148
	v_add_f32_e32 v50, 1.0, v50
	v_add_f32_e32 v51, 1.0, v51
	v_rcp_f32_e32 v50, v50
	v_rcp_f32_e32 v51, v51
	s_nop 0
	v_pk_mul_f32 v[46:47], v[46:47], v[50:51]
	s_nop 0
	v_pk_mul_f32 v[42:43], v[46:47], v[42:43]
	s_nop 0
	v_cvt_pk_bf16_f32 v42, v42, v43
	v_mul_f32_e32 v43, 0xbfb8aa3b, v48
	v_exp_f32_e32 v43, v43
	s_nop 0
	v_add_f32_e32 v43, 1.0, v43
	v_rcp_f32_e32 v46, v43
	v_mul_f32_e32 v43, 0xbfb8aa3b, v49
	v_exp_f32_e32 v43, v43
	s_nop 0
	v_add_f32_e32 v43, 1.0, v43
	v_rcp_f32_e32 v47, v43
	s_nop 0
	v_pk_mul_f32 v[46:47], v[48:49], v[46:47]
	s_nop 0
	v_pk_mul_f32 v[44:45], v[46:47], v[44:45]
	s_nop 0
	v_cvt_pk_bf16_f32 v43, v44, v45
	v_mad_i64_i32 v[44:45], s[8:9], v52, s7, v[122:123]
	v_lshl_add_u64 v[44:45], v[44:45], 0, v[124:125]
	global_store_dwordx2 v[44:45], v[42:43], off
	v_mul_f32_e32 v42, 0xbfb8aa3b, v38
	v_mul_f32_e32 v43, 0xbfb8aa3b, v39
	v_exp_f32_e32 v42, v42
	v_exp_f32_e32 v43, v43
	v_add_f32_e32 v42, 1.0, v42
	v_add_f32_e32 v43, 1.0, v43
	v_rcp_f32_e32 v42, v42
	v_rcp_f32_e32 v43, v43
	s_nop 0
	v_pk_mul_f32 v[38:39], v[38:39], v[42:43]
	s_nop 0
	v_pk_mul_f32 v[34:35], v[38:39], v[34:35]
	s_nop 0
	v_cvt_pk_bf16_f32 v34, v34, v35
	v_mul_f32_e32 v35, 0xbfb8aa3b, v40
	v_exp_f32_e32 v35, v35
	s_nop 0
	v_add_f32_e32 v35, 1.0, v35
	v_rcp_f32_e32 v38, v35
	v_mul_f32_e32 v35, 0xbfb8aa3b, v41
	v_exp_f32_e32 v35, v35
	s_nop 0
	v_add_f32_e32 v35, 1.0, v35
	v_rcp_f32_e32 v39, v35
	s_nop 0
	v_pk_mul_f32 v[38:39], v[40:41], v[38:39]
	s_nop 0
	v_pk_mul_f32 v[36:37], v[38:39], v[36:37]
	s_nop 0
	v_cvt_pk_bf16_f32 v35, v36, v37
	global_store_dwordx2 v[44:45], v[34:35], off offset:32
	v_mul_f32_e32 v34, 0xbfb8aa3b, v30
; DI float sigmoidf_(float v) { return __builtin_amdgcn_rcpf(1.f + __expf(-v)); }
; #define WAIT_V(n) asm volatile("s_waitcnt vmcnt(" #n ")" ::: "memory")
; #define BAR __builtin_amdgcn_s_barrier()
; #define EPI_SCHED __builtin_amdgcn_sched_barrier(0)
; template <class EPI>
; DI void gemm_stream(const u16* __restrict__ A, const u16* __restrict__ Bt, const int K, const int nM, const int nN,
;                     const int bid, const int nb, const int tid, EPI epi) {
;     ...
;   WAIT_V(0);
;   if (wr == 0) BAR;
;   BAR;
; DI void gemm_gateup(const Params& p, int bid, int nb, int tid) {
;     ...
;     _Pragma("unroll") for (int ai = 0; ai < 2; ++ai) _Pragma("unroll") for (int m = 0; m < 4; ++m) _Pragma("unroll") for (int n = 0; n < 2; ++n) {
;       const int col = pn * 128 + wc * 32 + n * 16 + fq * 4;
;       const int row = brow + ai * HALF + wr * 64 + m * 16 + fr;
;       const f32x4 g = acc[ai][0][m][n], uu = acc[ai][1][m][n];
;       uint2 w;
;       w.x = pk2(g[0] * sigmoidf_(g[0]) * uu[0], g[1] * sigmoidf_(g[1]) * uu[1]);
;       w.y = pk2(g[2] * sigmoidf_(g[2]) * uu[2], g[3] * sigmoidf_(g[3]) * uu[3]);
;       *reinterpret_cast<uint2*>(C + (size_t)row * DFF + col) = w;
;       EPI_SCHED;
;     }
	v_mul_f32_e32 v35, 0xbfb8aa3b, v31
	v_exp_f32_e32 v34, v34
	v_exp_f32_e32 v35, v35
	v_add_u32_e32 v36, 0xa0, v148
	v_add_f32_e32 v34, 1.0, v34
	v_add_f32_e32 v35, 1.0, v35
	v_rcp_f32_e32 v34, v34
	v_rcp_f32_e32 v35, v35
	s_nop 0
	v_pk_mul_f32 v[30:31], v[30:31], v[34:35]
	s_nop 0
	v_pk_mul_f32 v[26:27], v[30:31], v[26:27]
	s_nop 0
	v_cvt_pk_bf16_f32 v26, v26, v27
	v_mul_f32_e32 v27, 0xbfb8aa3b, v32
	v_exp_f32_e32 v27, v27
	s_nop 0
	v_add_f32_e32 v27, 1.0, v27
	v_rcp_f32_e32 v30, v27
	v_mul_f32_e32 v27, 0xbfb8aa3b, v33
	v_exp_f32_e32 v27, v27
	s_nop 0
	v_add_f32_e32 v27, 1.0, v27
	v_rcp_f32_e32 v31, v27
	s_nop 0
	v_pk_mul_f32 v[30:31], v[32:33], v[30:31]
	s_nop 0
	v_pk_mul_f32 v[28:29], v[30:31], v[28:29]
	s_nop 0
	v_cvt_pk_bf16_f32 v27, v28, v29
	v_mad_i64_i32 v[28:29], s[8:9], v36, s7, v[122:123]
	v_lshl_add_u64 v[28:29], v[28:29], 0, v[124:125]
	global_store_dwordx2 v[28:29], v[26:27], off
	v_mul_f32_e32 v26, 0xbfb8aa3b, v22
	v_mul_f32_e32 v27, 0xbfb8aa3b, v23
	v_exp_f32_e32 v26, v26
	v_exp_f32_e32 v27, v27
	v_add_f32_e32 v26, 1.0, v26
	v_add_f32_e32 v27, 1.0, v27
	v_rcp_f32_e32 v26, v26
	v_rcp_f32_e32 v27, v27
	s_nop 0
	v_pk_mul_f32 v[22:23], v[22:23], v[26:27]
	s_nop 0
	v_pk_mul_f32 v[18:19], v[22:23], v[18:19]
	s_nop 0
	v_cvt_pk_bf16_f32 v18, v18, v19
	v_mul_f32_e32 v19, 0xbfb8aa3b, v24
	v_exp_f32_e32 v19, v19
	s_nop 0
	v_add_f32_e32 v19, 1.0, v19
	v_rcp_f32_e32 v22, v19
	v_mul_f32_e32 v19, 0xbfb8aa3b, v25
	v_exp_f32_e32 v19, v19
	s_nop 0
	v_add_f32_e32 v19, 1.0, v19
	v_rcp_f32_e32 v23, v19
	s_nop 0
	v_pk_mul_f32 v[22:23], v[24:25], v[22:23]
	s_nop 0
	v_pk_mul_f32 v[20:21], v[22:23], v[20:21]
	s_nop 0
	v_cvt_pk_bf16_f32 v19, v20, v21
	global_store_dwordx2 v[28:29], v[18:19], off offset:32
	v_mul_f32_e32 v18, 0xbfb8aa3b, v14
	v_mul_f32_e32 v19, 0xbfb8aa3b, v15
	v_exp_f32_e32 v18, v18
	v_exp_f32_e32 v19, v19
	v_add_u32_e32 v20, 0xb0, v148
	v_add_f32_e32 v18, 1.0, v18
	v_add_f32_e32 v19, 1.0, v19
	v_rcp_f32_e32 v18, v18
	v_rcp_f32_e32 v19, v19
	s_nop 0
	v_pk_mul_f32 v[14:15], v[14:15], v[18:19]
	s_nop 0
	v_pk_mul_f32 v[10:11], v[14:15], v[10:11]
	s_nop 0
	v_cvt_pk_bf16_f32 v10, v10, v11
	v_mul_f32_e32 v11, 0xbfb8aa3b, v16
	v_exp_f32_e32 v11, v11
	s_nop 0
	v_add_f32_e32 v11, 1.0, v11
	v_rcp_f32_e32 v14, v11
	v_mul_f32_e32 v11, 0xbfb8aa3b, v17
	v_exp_f32_e32 v11, v11
	s_nop 0
	v_add_f32_e32 v11, 1.0, v11
	v_rcp_f32_e32 v15, v11
	s_nop 0
	v_pk_mul_f32 v[14:15], v[16:17], v[14:15]
	s_nop 0
	v_pk_mul_f32 v[12:13], v[14:15], v[12:13]
	s_nop 0
	v_cvt_pk_bf16_f32 v11, v12, v13
	v_mad_i64_i32 v[12:13], s[8:9], v20, s7, v[122:123]
	v_lshl_add_u64 v[12:13], v[12:13], 0, v[124:125]
	global_store_dwordx2 v[12:13], v[10:11], off
	v_mul_f32_e32 v10, 0xbfb8aa3b, v6
	v_mul_f32_e32 v11, 0xbfb8aa3b, v7
	v_exp_f32_e32 v10, v10
	v_exp_f32_e32 v11, v11
	v_add_f32_e32 v10, 1.0, v10
	v_add_f32_e32 v11, 1.0, v11
	v_rcp_f32_e32 v10, v10
	v_rcp_f32_e32 v11, v11
	s_nop 0
	v_pk_mul_f32 v[6:7], v[6:7], v[10:11]
	s_nop 0
	v_pk_mul_f32 v[2:3], v[6:7], v[2:3]
	s_nop 0
	v_cvt_pk_bf16_f32 v2, v2, v3
	v_mul_f32_e32 v3, 0xbfb8aa3b, v8
	v_exp_f32_e32 v3, v3
	s_nop 0
	v_add_f32_e32 v3, 1.0, v3
	v_rcp_f32_e32 v6, v3
	v_mul_f32_e32 v3, 0xbfb8aa3b, v9
	v_exp_f32_e32 v3, v3
	s_nop 0
	v_add_f32_e32 v3, 1.0, v3
	v_rcp_f32_e32 v7, v3
	s_nop 0
	v_pk_mul_f32 v[6:7], v[8:9], v[6:7]
	s_nop 0
	v_pk_mul_f32 v[4:5], v[6:7], v[4:5]
	s_nop 0
	v_cvt_pk_bf16_f32 v3, v4, v5
	global_store_dwordx2 v[12:13], v[2:3], off offset:32
	s_and_b64 vcc, exec, s[0:1]
	s_mov_b32 s8, s5
	s_mov_b32 s9, s6
	s_mov_b32 s7, s4
	s_cbranch_vccz .LBB0_43
	s_waitcnt vmcnt(0)
	s_movk_i32 s0, 0x100
	v_cmp_gt_u32_e32 vcc, s0, v239
	s_and_saveexec_b64 s[0:1], vcc
	s_cbranch_execz .LBB0_50
	s_barrier

; template <class EPI>
; DI void gemm_stream(const u16* __restrict__ A, const u16* __restrict__ Bt, const int K, const int nM, const int nN,
;                     const int bid, const int nb, const int tid, EPI epi) {
;     ...
;     for (int t = 0; t < nt; t += 2) {
;       const bool inside = (t + 2 < nt);
;       const int brs = inside ? brow : brow2, bcs = inside ? bcol : bcol2, t2 = inside ? t + 2 : 0;
.LBB0_132:
	v_or_b32_e32 v131, 0x10000, v167
	v_add_u32_e32 v136, 0x10400, v167
	v_add_u32_e32 v140, 0x10800, v167
	v_add_u32_e32 v144, 0x10c00, v167
	s_add_i32 s11, s10, 2
	ds_read_b128 v[132:135], v131
	ds_read_b128 v[136:139], v136
	ds_read_b128 v[140:143], v140
	ds_read_b128 v[144:147], v144
	s_cmp_lt_u32 s10, 30
	s_cselect_b32 s12, s8, s5
	s_cselect_b32 s13, s7, s6
	s_cselect_b32 s14, s9, 0
	s_lshl_b32 s13, s13, 11
	s_lshl_b32 s12, s12, 11
	s_or_b32 s15, s14, 64
	s_add_i32 s17, s12, s14
	s_or_b32 s18, s13, 0x40000
	s_add_i32 s16, s13, s14
	s_add_i32 s13, s15, s13
	s_add_i32 s12, s15, s12
	s_lshl_b32 s17, s17, 1
	s_add_i32 s19, s18, s14
	s_add_i32 s18, s18, s15
	s_addk_i32 s9, 0x80
	s_lshl_b32 s16, s16, 1
	s_lshl_b32 s14, s13, 1
	s_lshl_b32 s13, s12, 1
	s_lshl_b32 s15, s19, 1
	s_add_i32 s19, s17, 0x80000
	s_lshl_b32 s12, s18, 1
	s_cmp_gt_u32 s10, 29
	v_add_u32_e32 v148, 0xc000, v0
	v_add_u32_e32 v131, 0xfffc0000, v130
	v_readfirstlane_b32 s10, v148
	s_mov_b32 m0, s10
	ds_read_b128 v[170:173], v166
	ds_read_b128 v[174:177], v166 offset:1024
	ds_read_b128 v[180:183], v166 offset:2048
	ds_read_b128 v[184:187], v166 offset:3072
	ds_read_b128 v[188:191], v166 offset:4096
	ds_read_b128 v[192:195], v166 offset:5120
	ds_read_b128 v[196:199], v166 offset:6144
	ds_read_b128 v[200:203], v166 offset:7168
	global_load_lds_dwordx4 v131, s[86:87]
	s_waitcnt lgkmcnt(8)
	v_or_b32_e32 v131, 0x14000, v167
	v_add_u32_e32 v148, 0x14400, v167
	ds_read_b128 v[204:207], v131
	ds_read_b128 v[208:211], v148
	v_add_u32_e32 v131, 0x14800, v167
	v_add_u32_e32 v148, 0x14c00, v167
	ds_read_b128 v[212:215], v131
	ds_read_b128 v[216:219], v148
	v_add_u32_e32 v131, 0xe000, v0
	s_nop 0
	v_readfirstlane_b32 s10, v131
	s_mov_b32 m0, s10
	s_nop 0
	global_load_lds_dwordx4 v130, s[86:87]
	s_waitcnt vmcnt(8)
	s_waitcnt lgkmcnt(0)
	s_barrier
	v_mfma_f32_16x16x32_bf16 v[98:101], v[132:135], v[170:173], v[98:101]
	v_mfma_f32_16x16x32_bf16 v[102:105], v[140:143], v[170:173], v[102:105]
	v_mfma_f32_16x16x32_bf16 v[126:129], v[132:135], v[180:183], v[126:129]
	v_mfma_f32_16x16x32_bf16 v[122:125], v[140:143], v[180:183], v[122:125]
	v_mfma_f32_16x16x32_bf16 v[118:121], v[132:135], v[188:191], v[118:121]
	v_mfma_f32_16x16x32_bf16 v[114:117], v[140:143], v[188:191], v[114:117]
	v_mfma_f32_16x16x32_bf16 v[110:113], v[132:135], v[196:199], v[110:113]
	v_mfma_f32_16x16x32_bf16 v[106:109], v[140:143], v[196:199], v[106:109]
	v_mfma_f32_16x16x32_bf16 v[98:101], v[136:139], v[174:177], v[98:101]
	v_mfma_f32_16x16x32_bf16 v[102:105], v[144:147], v[174:177], v[102:105]
	v_mfma_f32_16x16x32_bf16 v[126:129], v[136:139], v[184:187], v[126:129]
	v_mfma_f32_16x16x32_bf16 v[122:125], v[144:147], v[184:187], v[122:125]
	v_mfma_f32_16x16x32_bf16 v[118:121], v[136:139], v[192:195], v[118:121]
	v_mfma_f32_16x16x32_bf16 v[114:117], v[144:147], v[192:195], v[114:117]
	v_mfma_f32_16x16x32_bf16 v[110:113], v[136:139], v[200:203], v[110:113]
	v_mfma_f32_16x16x32_bf16 v[106:109], v[144:147], v[200:203], v[106:109]
	v_mfma_f32_16x16x32_bf16 v[66:69], v[204:207], v[170:173], v[66:69]
	v_mfma_f32_16x16x32_bf16 v[70:73], v[212:215], v[170:173], v[70:73]
	v_mfma_f32_16x16x32_bf16 v[74:77], v[204:207], v[180:183], v[74:77]
	v_mfma_f32_16x16x32_bf16 v[78:81], v[212:215], v[180:183], v[78:81]
	v_mfma_f32_16x16x32_bf16 v[82:85], v[204:207], v[188:191], v[82:85]
	v_mfma_f32_16x16x32_bf16 v[86:89], v[212:215], v[188:191], v[86:89]
	v_mfma_f32_16x16x32_bf16 v[90:93], v[204:207], v[196:199], v[90:93]
	v_mfma_f32_16x16x32_bf16 v[94:97], v[212:215], v[196:199], v[94:97]
	v_mfma_f32_16x16x32_bf16 v[66:69], v[208:211], v[174:177], v[66:69]
	v_mfma_f32_16x16x32_bf16 v[70:73], v[216:219], v[174:177], v[70:73]
	v_mfma_f32_16x16x32_bf16 v[74:77], v[208:211], v[184:187], v[74:77]
	v_mfma_f32_16x16x32_bf16 v[78:81], v[216:219], v[184:187], v[78:81]
	v_mfma_f32_16x16x32_bf16 v[82:85], v[208:211], v[192:195], v[82:85]
	v_mfma_f32_16x16x32_bf16 v[86:89], v[216:219], v[192:195], v[86:89]
	v_mfma_f32_16x16x32_bf16 v[90:93], v[208:211], v[200:203], v[90:93]
	v_mfma_f32_16x16x32_bf16 v[94:97], v[216:219], v[200:203], v[94:97]
	s_barrier
	v_readfirstlane_b32 s10, v152
	v_add_u32_e32 v131, s16, v150
	s_mov_b32 m0, s10
	v_readfirstlane_b32 s10, v153
	global_load_lds_dwordx4 v131, s[88:89]
	v_add_u32_e32 v131, s16, v151
	s_mov_b32 m0, s10
	s_nop 0
	global_load_lds_dwordx4 v131, s[88:89]
	v_readfirstlane_b32 s10, v0
	v_add_u32_e32 v131, s17, v150
	s_mov_b32 m0, s10
	v_readfirstlane_b32 s10, v154
	ds_read_b128 v[170:173], v166 offset:16384
	ds_read_b128 v[174:177], v166 offset:17408
	ds_read_b128 v[180:183], v166 offset:18432
	ds_read_b128 v[184:187], v166 offset:19456
	ds_read_b128 v[188:191], v166 offset:20480
	ds_read_b128 v[192:195], v166 offset:21504
	ds_read_b128 v[196:199], v166 offset:22528
	ds_read_b128 v[200:203], v166 offset:23552
	global_load_lds_dwordx4 v131, s[86:87]
	v_add_u32_e32 v131, s17, v151
	s_mov_b32 m0, s10
	s_nop 0
	global_load_lds_dwordx4 v131, s[86:87]
	v_readfirstlane_b32 s10, v155
	v_add_u32_e32 v131, s15, v150
	s_mov_b32 m0, s10
	v_readfirstlane_b32 s10, v156
	global_load_lds_dwordx4 v131, s[88:89]
	v_add_u32_e32 v131, s15, v151
	s_mov_b32 m0, s10
	s_nop 0
	global_load_lds_dwordx4 v131, s[88:89]
	s_waitcnt vmcnt(8)
	s_waitcnt lgkmcnt(0)
	s_barrier
	v_mfma_f32_16x16x32_bf16 v[34:37], v[132:135], v[170:173], v[34:37]
	v_mfma_f32_16x16x32_bf16 v[38:41], v[140:143], v[170:173], v[38:41]
	v_mfma_f32_16x16x32_bf16 v[42:45], v[132:135], v[180:183], v[42:45]
	v_mfma_f32_16x16x32_bf16 v[46:49], v[140:143], v[180:183], v[46:49]
	v_mfma_f32_16x16x32_bf16 v[50:53], v[132:135], v[188:191], v[50:53]
	v_mfma_f32_16x16x32_bf16 v[54:57], v[140:143], v[188:191], v[54:57]
	v_mfma_f32_16x16x32_bf16 v[58:61], v[132:135], v[196:199], v[58:61]
	v_mfma_f32_16x16x32_bf16 v[62:65], v[140:143], v[196:199], v[62:65]
	v_mfma_f32_16x16x32_bf16 v[34:37], v[136:139], v[174:177], v[34:37]
	v_mfma_f32_16x16x32_bf16 v[38:41], v[144:147], v[174:177], v[38:41]
	v_mfma_f32_16x16x32_bf16 v[42:45], v[136:139], v[184:187], v[42:45]
	v_mfma_f32_16x16x32_bf16 v[46:49], v[144:147], v[184:187], v[46:49]
	v_mfma_f32_16x16x32_bf16 v[50:53], v[136:139], v[192:195], v[50:53]
	v_mfma_f32_16x16x32_bf16 v[54:57], v[144:147], v[192:195], v[54:57]
	v_mfma_f32_16x16x32_bf16 v[58:61], v[136:139], v[200:203], v[58:61]
	v_mfma_f32_16x16x32_bf16 v[62:65], v[144:147], v[200:203], v[62:65]
	v_mfma_f32_16x16x32_bf16 v[2:5], v[204:207], v[170:173], v[2:5]
	v_mfma_f32_16x16x32_bf16 v[6:9], v[212:215], v[170:173], v[6:9]
	v_mfma_f32_16x16x32_bf16 v[10:13], v[204:207], v[180:183], v[10:13]
	v_mfma_f32_16x16x32_bf16 v[14:17], v[212:215], v[180:183], v[14:17]
	v_mfma_f32_16x16x32_bf16 v[18:21], v[204:207], v[188:191], v[18:21]
	v_mfma_f32_16x16x32_bf16 v[22:25], v[212:215], v[188:191], v[22:25]
	v_mfma_f32_16x16x32_bf16 v[26:29], v[204:207], v[196:199], v[26:29]
	v_mfma_f32_16x16x32_bf16 v[30:33], v[212:215], v[196:199], v[30:33]
	v_mfma_f32_16x16x32_bf16 v[2:5], v[208:211], v[174:177], v[2:5]
	v_mfma_f32_16x16x32_bf16 v[6:9], v[216:219], v[174:177], v[6:9]
	v_mfma_f32_16x16x32_bf16 v[10:13], v[208:211], v[184:187], v[10:13]
	v_mfma_f32_16x16x32_bf16 v[14:17], v[216:219], v[184:187], v[14:17]
	v_mfma_f32_16x16x32_bf16 v[18:21], v[208:211], v[192:195], v[18:21]
	v_mfma_f32_16x16x32_bf16 v[22:25], v[216:219], v[192:195], v[22:25]
	v_mfma_f32_16x16x32_bf16 v[26:29], v[208:211], v[200:203], v[26:29]
	v_mfma_f32_16x16x32_bf16 v[30:33], v[216:219], v[200:203], v[30:33]
	s_barrier
	v_or_b32_e32 v131, 0x18000, v167
	v_add_u32_e32 v136, 0x18400, v167
	ds_read_b128 v[132:135], v131
	ds_read_b128 v[136:139], v136
	v_add_u32_e32 v131, 0x18800, v167
	v_add_u32_e32 v144, 0x18c00, v167
	ds_read_b128 v[140:143], v131
	ds_read_b128 v[144:147], v144
	v_readfirstlane_b32 s10, v157
	v_add_u32_e32 v131, s19, v150
	s_mov_b32 m0, s10
	v_readfirstlane_b32 s10, v158
	ds_read_b128 v[170:173], v166 offset:32768
	ds_read_b128 v[174:177], v166 offset:33792
	ds_read_b128 v[180:183], v166 offset:34816
	ds_read_b128 v[184:187], v166 offset:35840
	ds_read_b128 v[188:191], v166 offset:36864
	ds_read_b128 v[192:195], v166 offset:37888
	ds_read_b128 v[196:199], v166 offset:38912
	ds_read_b128 v[200:203], v166 offset:39936
	global_load_lds_dwordx4 v131, s[86:87]
	s_waitcnt lgkmcnt(8)
	v_or_b32_e32 v131, 0x1c000, v167
	v_add_u32_e32 v148, 0x1c400, v167
	ds_read_b128 v[204:207], v131
	ds_read_b128 v[208:211], v148
	v_add_u32_e32 v131, 0x1c800, v167
	v_add_u32_e32 v148, 0x1cc00, v167
	ds_read_b128 v[212:215], v131
	ds_read_b128 v[216:219], v148
	v_add_u32_e32 v131, s19, v151
	s_mov_b32 m0, s10
	s_nop 0
	global_load_lds_dwordx4 v131, s[86:87]
	s_waitcnt vmcnt(8)
	s_waitcnt lgkmcnt(0)
	s_barrier
	v_mfma_f32_16x16x32_bf16 v[98:101], v[132:135], v[170:173], v[98:101]
	v_mfma_f32_16x16x32_bf16 v[102:105], v[140:143], v[170:173], v[102:105]
	v_mfma_f32_16x16x32_bf16 v[126:129], v[132:135], v[180:183], v[126:129]
	v_mfma_f32_16x16x32_bf16 v[122:125], v[140:143], v[180:183], v[122:125]
	v_mfma_f32_16x16x32_bf16 v[118:121], v[132:135], v[188:191], v[118:121]
	v_mfma_f32_16x16x32_bf16 v[114:117], v[140:143], v[188:191], v[114:117]
	v_mfma_f32_16x16x32_bf16 v[110:113], v[132:135], v[196:199], v[110:113]
	v_mfma_f32_16x16x32_bf16 v[106:109], v[140:143], v[196:199], v[106:109]
	v_mfma_f32_16x16x32_bf16 v[98:101], v[136:139], v[174:177], v[98:101]
	v_mfma_f32_16x16x32_bf16 v[102:105], v[144:147], v[174:177], v[102:105]
	v_mfma_f32_16x16x32_bf16 v[126:129], v[136:139], v[184:187], v[126:129]
	v_mfma_f32_16x16x32_bf16 v[122:125], v[144:147], v[184:187], v[122:125]
	v_mfma_f32_16x16x32_bf16 v[118:121], v[136:139], v[192:195], v[118:121]
	v_mfma_f32_16x16x32_bf16 v[114:117], v[144:147], v[192:195], v[114:117]
	v_mfma_f32_16x16x32_bf16 v[110:113], v[136:139], v[200:203], v[110:113]
	v_mfma_f32_16x16x32_bf16 v[106:109], v[144:147], v[200:203], v[106:109]
	v_mfma_f32_16x16x32_bf16 v[66:69], v[204:207], v[170:173], v[66:69]
	v_mfma_f32_16x16x32_bf16 v[70:73], v[212:215], v[170:173], v[70:73]
	v_mfma_f32_16x16x32_bf16 v[74:77], v[204:207], v[180:183], v[74:77]
	v_mfma_f32_16x16x32_bf16 v[78:81], v[212:215], v[180:183], v[78:81]
	v_mfma_f32_16x16x32_bf16 v[82:85], v[204:207], v[188:191], v[82:85]
	v_mfma_f32_16x16x32_bf16 v[86:89], v[212:215], v[188:191], v[86:89]
	v_mfma_f32_16x16x32_bf16 v[90:93], v[204:207], v[196:199], v[90:93]
	v_mfma_f32_16x16x32_bf16 v[94:97], v[212:215], v[196:199], v[94:97]
	v_mfma_f32_16x16x32_bf16 v[66:69], v[208:211], v[174:177], v[66:69]
	v_mfma_f32_16x16x32_bf16 v[70:73], v[216:219], v[174:177], v[70:73]
	v_mfma_f32_16x16x32_bf16 v[74:77], v[208:211], v[184:187], v[74:77]
	v_mfma_f32_16x16x32_bf16 v[78:81], v[216:219], v[184:187], v[78:81]
	v_mfma_f32_16x16x32_bf16 v[82:85], v[208:211], v[192:195], v[82:85]
	v_mfma_f32_16x16x32_bf16 v[86:89], v[216:219], v[192:195], v[86:89]
	v_mfma_f32_16x16x32_bf16 v[90:93], v[208:211], v[200:203], v[90:93]
	v_mfma_f32_16x16x32_bf16 v[94:97], v[216:219], v[200:203], v[94:97]
	s_barrier
; DI void gemm_resid(const u16* A, const u16* Bt, int K, const float* xin, float* xout, int bid, int nb, int tid) {
;     ...
;     for (int ai = 0; ai < 2; ++ai)
; #pragma unroll
;       for (int bj = 0; bj < 2; ++bj) {
;         float4 xi[4][2];
; #pragma unroll
;         for (int m = 0; m < 4; ++m)
; #pragma unroll
;           for (int n = 0; n < 2; ++n) xi[m][n] = *reinterpret_cast<const float4*>(xin + (size_t)ACC_ROW * 2048 + ACC_COL);
	v_readfirstlane_b32 s10, v159
	v_add_u32_e32 v131, s14, v150
	s_mov_b32 m0, s10
	v_readfirstlane_b32 s10, v160
	global_load_lds_dwordx4 v131, s[88:89]
	v_add_u32_e32 v131, s14, v151
	s_mov_b32 m0, s10
	s_nop 0
	global_load_lds_dwordx4 v131, s[88:89]
	v_readfirstlane_b32 s10, v161
	v_add_u32_e32 v131, s13, v150
	s_mov_b32 m0, s10
	v_readfirstlane_b32 s10, v162
	ds_read_b128 v[170:173], v166 offset:49152
	ds_read_b128 v[174:177], v166 offset:50176
	ds_read_b128 v[180:183], v166 offset:51200
	ds_read_b128 v[184:187], v166 offset:52224
	ds_read_b128 v[188:191], v166 offset:53248
	ds_read_b128 v[192:195], v166 offset:54272
	ds_read_b128 v[196:199], v166 offset:55296
	ds_read_b128 v[200:203], v166 offset:56320
	global_load_lds_dwordx4 v131, s[86:87]
	v_add_u32_e32 v131, s13, v151
	s_mov_b32 m0, s10
	s_nop 0
	global_load_lds_dwordx4 v131, s[86:87]
	v_readfirstlane_b32 s10, v163
	v_add_u32_e32 v131, s12, v150
	s_mov_b32 m0, s10
	v_readfirstlane_b32 s10, v165
	global_load_lds_dwordx4 v131, s[88:89]
	v_add_u32_e32 v131, s12, v151
	s_mov_b32 m0, s10
	s_nop 0
	global_load_lds_dwordx4 v131, s[88:89]
	s_waitcnt vmcnt(8)
	s_waitcnt lgkmcnt(0)
	s_barrier
	v_mfma_f32_16x16x32_bf16 v[34:37], v[132:135], v[170:173], v[34:37]
	v_mfma_f32_16x16x32_bf16 v[38:41], v[140:143], v[170:173], v[38:41]
	v_mfma_f32_16x16x32_bf16 v[42:45], v[132:135], v[180:183], v[42:45]
	v_mfma_f32_16x16x32_bf16 v[46:49], v[140:143], v[180:183], v[46:49]
	v_mfma_f32_16x16x32_bf16 v[50:53], v[132:135], v[188:191], v[50:53]
	v_mfma_f32_16x16x32_bf16 v[54:57], v[140:143], v[188:191], v[54:57]
	v_mfma_f32_16x16x32_bf16 v[58:61], v[132:135], v[196:199], v[58:61]
	v_mfma_f32_16x16x32_bf16 v[62:65], v[140:143], v[196:199], v[62:65]
	v_mfma_f32_16x16x32_bf16 v[34:37], v[136:139], v[174:177], v[34:37]
	v_mfma_f32_16x16x32_bf16 v[38:41], v[144:147], v[174:177], v[38:41]
	v_mfma_f32_16x16x32_bf16 v[42:45], v[136:139], v[184:187], v[42:45]
	v_mfma_f32_16x16x32_bf16 v[46:49], v[144:147], v[184:187], v[46:49]
	v_mfma_f32_16x16x32_bf16 v[50:53], v[136:139], v[192:195], v[50:53]
	v_mfma_f32_16x16x32_bf16 v[54:57], v[144:147], v[192:195], v[54:57]
	v_mfma_f32_16x16x32_bf16 v[58:61], v[136:139], v[200:203], v[58:61]
	v_mfma_f32_16x16x32_bf16 v[62:65], v[144:147], v[200:203], v[62:65]
	v_mfma_f32_16x16x32_bf16 v[2:5], v[204:207], v[170:173], v[2:5]
	v_mfma_f32_16x16x32_bf16 v[6:9], v[212:215], v[170:173], v[6:9]
	v_mfma_f32_16x16x32_bf16 v[10:13], v[204:207], v[180:183], v[10:13]
	v_mfma_f32_16x16x32_bf16 v[14:17], v[212:215], v[180:183], v[14:17]
	v_mfma_f32_16x16x32_bf16 v[18:21], v[204:207], v[188:191], v[18:21]
	v_mfma_f32_16x16x32_bf16 v[22:25], v[212:215], v[188:191], v[22:25]
	v_mfma_f32_16x16x32_bf16 v[26:29], v[204:207], v[196:199], v[26:29]
	v_mfma_f32_16x16x32_bf16 v[30:33], v[212:215], v[196:199], v[30:33]
	v_mfma_f32_16x16x32_bf16 v[2:5], v[208:211], v[174:177], v[2:5]
	v_mfma_f32_16x16x32_bf16 v[6:9], v[216:219], v[174:177], v[6:9]
	v_mfma_f32_16x16x32_bf16 v[10:13], v[208:211], v[184:187], v[10:13]
	v_mfma_f32_16x16x32_bf16 v[14:17], v[216:219], v[184:187], v[14:17]
	v_mfma_f32_16x16x32_bf16 v[18:21], v[208:211], v[192:195], v[18:21]
	v_mfma_f32_16x16x32_bf16 v[22:25], v[216:219], v[192:195], v[22:25]
	v_mfma_f32_16x16x32_bf16 v[26:29], v[208:211], v[200:203], v[26:29]
	v_mfma_f32_16x16x32_bf16 v[30:33], v[216:219], v[200:203], v[30:33]
	v_add_u32_e32 v130, 0x100, v130
	s_mov_b32 s10, s11
	s_barrier
	s_cbranch_scc0 .LBB0_132
	v_mov_b32_e32 v131, v239
	s_nop 0
	v_ashrrev_i32_e32 v130, 2, v131
	v_and_b32_e32 v130, 0xffffffc0, v130
	v_and_or_b32 v132, v131, 15, s8
	v_add_u32_e32 v130, v132, v130
	v_lshrrev_b32_e32 v132, 1, v131
	v_lshrrev_b32_e32 v131, 2, v131
	v_and_b32_e32 v132, 0x60, v132
	v_and_b32_e32 v131, 12, v131
	v_or3_b32 v132, v132, v131, s7
	v_ashrrev_i32_e32 v131, 31, v130
	v_ashrrev_i32_e32 v133, 31, v132
	v_lshlrev_b64 v[134:135], 13, v[130:131]
	v_lshl_add_u64 v[136:137], s[48:49], 0, v[134:135]
	v_lshlrev_b64 v[132:133], 2, v[132:133]
	v_lshl_add_u64 v[142:143], v[136:137], 0, v[132:133]
	v_or_b32_e32 v136, 16, v130
	v_ashrrev_i32_e32 v137, 31, v136
	v_lshlrev_b64 v[136:137], 13, v[136:137]
	v_lshl_add_u64 v[138:139], s[48:49], 0, v[136:137]
	v_lshl_add_u64 v[144:145], v[138:139], 0, v[132:133]
	v_or_b32_e32 v138, 32, v130
	v_ashrrev_i32_e32 v139, 31, v138
	v_lshlrev_b64 v[170:171], 13, v[138:139]
	v_lshl_add_u64 v[138:139], s[48:49], 0, v[170:171]
	v_lshl_add_u64 v[146:147], v[138:139], 0, v[132:133]
	v_or_b32_e32 v138, 48, v130
	v_ashrrev_i32_e32 v139, 31, v138
	v_lshlrev_b64 v[172:173], 13, v[138:139]
	v_lshl_add_u64 v[134:135], s[72:73], 0, v[134:135]
	v_lshl_add_u64 v[138:139], s[48:49], 0, v[172:173]
	v_lshl_add_u64 v[140:141], v[134:135], 0, v[132:133]
	v_lshl_add_u64 v[134:135], s[72:73], 0, v[136:137]
	v_lshl_add_u64 v[148:149], v[138:139], 0, v[132:133]
	v_lshl_add_u64 v[138:139], v[134:135], 0, v[132:133]
	v_lshl_add_u64 v[134:135], s[72:73], 0, v[170:171]
	v_lshl_add_u64 v[136:137], v[134:135], 0, v[132:133]
	v_lshl_add_u64 v[134:135], s[72:73], 0, v[172:173]
	v_lshl_add_u64 v[134:135], v[134:135], 0, v[132:133]
	global_load_dwordx4 v[180:183], v[148:149], off offset:64
	global_load_dwordx4 v[184:187], v[148:149], off
	global_load_dwordx4 v[188:191], v[146:147], off offset:64
	global_load_dwordx4 v[192:195], v[146:147], off
	global_load_dwordx4 v[196:199], v[144:145], off offset:64
	global_load_dwordx4 v[200:203], v[144:145], off
	global_load_dwordx4 v[204:207], v[142:143], off offset:64
	global_load_dwordx4 v[208:211], v[142:143], off
	s_waitcnt vmcnt(0)
; #define EPI_SCHED __builtin_amdgcn_sched_barrier(0)
; DI void gemm_resid(const u16* A, const u16* Bt, int K, const float* xin, float* xout, int bid, int nb, int tid) {
;     ...
;     for (int ai = 0; ai < 2; ++ai)
; #pragma unroll
;       for (int bj = 0; bj < 2; ++bj) {
;         float4 xi[4][2];
; #pragma unroll
;         for (int m = 0; m < 4; ++m)
; #pragma unroll
;           for (int n = 0; n < 2; ++n) xi[m][n] = *reinterpret_cast<const float4*>(xin + (size_t)ACC_ROW * 2048 + ACC_COL);
; #pragma unroll
;         for (int m = 0; m < 4; ++m)
; #pragma unroll
;           for (int n = 0; n < 2; ++n) {
;             const f32x4 v = acc[ai][bj][m][n];
;             float4 r; r.x = xi[m][n].x + v[0]; r.y = xi[m][n].y + v[1]; r.z = xi[m][n].z + v[2]; r.w = xi[m][n].w + v[3];
;             *reinterpret_cast<float4*>(xout + (size_t)ACC_ROW * 2048 + ACC_COL) = r;
;           }
;         EPI_SCHED;
;       }
	v_pk_add_f32 v[106:107], v[106:107], v[180:181]
	v_pk_add_f32 v[108:109], v[108:109], v[182:183]
	v_pk_add_f32 v[110:111], v[110:111], v[184:185]
	v_pk_add_f32 v[112:113], v[112:113], v[186:187]
	v_pk_add_f32 v[114:115], v[114:115], v[188:189]
	v_pk_add_f32 v[116:117], v[116:117], v[190:191]
	v_pk_add_f32 v[118:119], v[118:119], v[192:193]
	v_pk_add_f32 v[120:121], v[120:121], v[194:195]
	v_pk_add_f32 v[122:123], v[122:123], v[196:197]
	v_pk_add_f32 v[124:125], v[124:125], v[198:199]
	v_pk_add_f32 v[126:127], v[126:127], v[200:201]
	v_pk_add_f32 v[128:129], v[128:129], v[202:203]
	v_pk_add_f32 v[102:103], v[102:103], v[204:205]
	v_pk_add_f32 v[104:105], v[104:105], v[206:207]
	v_pk_add_f32 v[98:99], v[98:99], v[208:209]
	v_pk_add_f32 v[100:101], v[100:101], v[210:211]
	global_store_dwordx4 v[140:141], v[98:101], off
	global_store_dwordx4 v[140:141], v[102:105], off offset:64
	global_store_dwordx4 v[138:139], v[126:129], off
	global_store_dwordx4 v[138:139], v[122:125], off offset:64
	global_store_dwordx4 v[136:137], v[118:121], off
	global_store_dwordx4 v[136:137], v[114:117], off offset:64
	global_store_dwordx4 v[134:135], v[110:113], off
	global_store_dwordx4 v[134:135], v[106:109], off offset:64
	global_load_dwordx4 v[180:183], v[148:149], off offset:576
	global_load_dwordx4 v[184:187], v[148:149], off offset:512
	global_load_dwordx4 v[188:191], v[146:147], off offset:576
	global_load_dwordx4 v[192:195], v[146:147], off offset:512
	global_load_dwordx4 v[196:199], v[144:145], off offset:576
	global_load_dwordx4 v[200:203], v[144:145], off offset:512
	global_load_dwordx4 v[204:207], v[142:143], off offset:576
	global_load_dwordx4 v[208:211], v[142:143], off offset:512
	s_waitcnt vmcnt(0)
	v_pk_add_f32 v[94:95], v[94:95], v[180:181]
	v_pk_add_f32 v[96:97], v[96:97], v[182:183]
	v_pk_add_f32 v[90:91], v[90:91], v[184:185]
	v_pk_add_f32 v[92:93], v[92:93], v[186:187]
	v_pk_add_f32 v[86:87], v[86:87], v[188:189]
	v_pk_add_f32 v[88:89], v[88:89], v[190:191]
	v_pk_add_f32 v[82:83], v[82:83], v[192:193]
	v_pk_add_f32 v[84:85], v[84:85], v[194:195]
	v_pk_add_f32 v[78:79], v[78:79], v[196:197]
	v_pk_add_f32 v[80:81], v[80:81], v[198:199]
	v_pk_add_f32 v[74:75], v[74:75], v[200:201]
	v_pk_add_f32 v[76:77], v[76:77], v[202:203]
	v_pk_add_f32 v[70:71], v[70:71], v[204:205]
	v_pk_add_f32 v[72:73], v[72:73], v[206:207]
	v_pk_add_f32 v[66:67], v[66:67], v[208:209]
	v_pk_add_f32 v[68:69], v[68:69], v[210:211]
	global_store_dwordx4 v[140:141], v[66:69], off offset:512
	global_store_dwordx4 v[140:141], v[70:73], off offset:576
	global_store_dwordx4 v[138:139], v[74:77], off offset:512
	global_store_dwordx4 v[138:139], v[78:81], off offset:576
	global_store_dwordx4 v[136:137], v[82:85], off offset:512
	global_store_dwordx4 v[136:137], v[86:89], off offset:576
	global_store_dwordx4 v[134:135], v[90:93], off offset:512
	global_store_dwordx4 v[134:135], v[94:97], off offset:576
	v_add_u32_e32 v66, 0x80, v130
	v_ashrrev_i32_e32 v67, 31, v66
	v_lshlrev_b64 v[66:67], 13, v[66:67]
	v_lshl_add_u64 v[68:69], s[48:49], 0, v[66:67]
	v_lshl_add_u64 v[74:75], v[68:69], 0, v[132:133]
	v_add_u32_e32 v68, 0x90, v130
	v_ashrrev_i32_e32 v69, 31, v68
	v_lshlrev_b64 v[68:69], 13, v[68:69]
	v_lshl_add_u64 v[70:71], s[48:49], 0, v[68:69]
	v_lshl_add_u64 v[76:77], v[70:71], 0, v[132:133]
	v_add_u32_e32 v70, 0xa0, v130
	v_ashrrev_i32_e32 v71, 31, v70
	v_lshlrev_b64 v[82:83], 13, v[70:71]
	v_lshl_add_u64 v[70:71], s[48:49], 0, v[82:83]
	v_lshl_add_u64 v[78:79], v[70:71], 0, v[132:133]
	v_add_u32_e32 v70, 0xb0, v130
	v_ashrrev_i32_e32 v71, 31, v70
	v_lshlrev_b64 v[84:85], 13, v[70:71]
	v_lshl_add_u64 v[66:67], s[72:73], 0, v[66:67]
	v_lshl_add_u64 v[70:71], s[48:49], 0, v[84:85]
	v_lshl_add_u64 v[72:73], v[66:67], 0, v[132:133]
	v_lshl_add_u64 v[66:67], s[72:73], 0, v[68:69]
	v_lshl_add_u64 v[80:81], v[70:71], 0, v[132:133]
	v_lshl_add_u64 v[70:71], v[66:67], 0, v[132:133]
	v_lshl_add_u64 v[66:67], s[72:73], 0, v[82:83]
	v_lshl_add_u64 v[68:69], v[66:67], 0, v[132:133]
	v_lshl_add_u64 v[66:67], s[72:73], 0, v[84:85]
	v_lshl_add_u64 v[66:67], v[66:67], 0, v[132:133]
	global_load_dwordx4 v[180:183], v[80:81], off offset:64
	global_load_dwordx4 v[184:187], v[80:81], off
	global_load_dwordx4 v[188:191], v[78:79], off offset:64
	global_load_dwordx4 v[192:195], v[78:79], off
	global_load_dwordx4 v[196:199], v[76:77], off offset:64
	global_load_dwordx4 v[200:203], v[76:77], off
	global_load_dwordx4 v[204:207], v[74:75], off offset:64
	global_load_dwordx4 v[208:211], v[74:75], off
	s_waitcnt vmcnt(0)
; #define WAIT_V(n) asm volatile("s_waitcnt vmcnt(" #n ")" ::: "memory")
; #define BAR __builtin_amdgcn_s_barrier()
; #define EPI_SCHED __builtin_amdgcn_sched_barrier(0)
; template <class EPI>
; DI void gemm_stream(const u16* __restrict__ A, const u16* __restrict__ Bt, const int K, const int nM, const int nN,
;                     const int bid, const int nb, const int tid, EPI epi) {
;     ...
;   WAIT_V(0);
;   if (wr == 0) BAR;
;   BAR;
; DI void gemm_resid(const u16* A, const u16* Bt, int K, const float* xin, float* xout, int bid, int nb, int tid) {
;     ...
;           for (int n = 0; n < 2; ++n) xi[m][n] = *reinterpret_cast<const float4*>(xin + (size_t)ACC_ROW * 2048 + ACC_COL);
; #pragma unroll
;         for (int m = 0; m < 4; ++m)
; #pragma unroll
;           for (int n = 0; n < 2; ++n) {
;             const f32x4 v = acc[ai][bj][m][n];
;             float4 r; r.x = xi[m][n].x + v[0]; r.y = xi[m][n].y + v[1]; r.z = xi[m][n].z + v[2]; r.w = xi[m][n].w + v[3];
;             *reinterpret_cast<float4*>(xout + (size_t)ACC_ROW * 2048 + ACC_COL) = r;
;           }
;         EPI_SCHED;
;       }
	v_pk_add_f32 v[62:63], v[62:63], v[180:181]
	v_pk_add_f32 v[64:65], v[64:65], v[182:183]
	v_pk_add_f32 v[58:59], v[58:59], v[184:185]
	v_pk_add_f32 v[60:61], v[60:61], v[186:187]
	v_pk_add_f32 v[54:55], v[54:55], v[188:189]
	v_pk_add_f32 v[56:57], v[56:57], v[190:191]
	v_pk_add_f32 v[50:51], v[50:51], v[192:193]
	v_pk_add_f32 v[52:53], v[52:53], v[194:195]
	v_pk_add_f32 v[46:47], v[46:47], v[196:197]
	v_pk_add_f32 v[48:49], v[48:49], v[198:199]
	v_pk_add_f32 v[42:43], v[42:43], v[200:201]
	v_pk_add_f32 v[44:45], v[44:45], v[202:203]
	v_pk_add_f32 v[38:39], v[38:39], v[204:205]
	v_pk_add_f32 v[40:41], v[40:41], v[206:207]
	v_pk_add_f32 v[34:35], v[34:35], v[208:209]
	v_pk_add_f32 v[36:37], v[36:37], v[210:211]
	global_store_dwordx4 v[72:73], v[34:37], off
	global_store_dwordx4 v[72:73], v[38:41], off offset:64
	global_store_dwordx4 v[70:71], v[42:45], off
	global_store_dwordx4 v[70:71], v[46:49], off offset:64
	global_store_dwordx4 v[68:69], v[50:53], off
	global_store_dwordx4 v[68:69], v[54:57], off offset:64
	global_store_dwordx4 v[66:67], v[58:61], off
	global_store_dwordx4 v[66:67], v[62:65], off offset:64
	global_load_dwordx4 v[180:183], v[80:81], off offset:576
	global_load_dwordx4 v[184:187], v[80:81], off offset:512
	global_load_dwordx4 v[188:191], v[78:79], off offset:576
	global_load_dwordx4 v[192:195], v[78:79], off offset:512
	global_load_dwordx4 v[196:199], v[76:77], off offset:576
	global_load_dwordx4 v[200:203], v[76:77], off offset:512
	global_load_dwordx4 v[204:207], v[74:75], off offset:576
	global_load_dwordx4 v[208:211], v[74:75], off offset:512
	s_waitcnt vmcnt(0)
	v_pk_add_f32 v[30:31], v[30:31], v[180:181]
	v_pk_add_f32 v[32:33], v[32:33], v[182:183]
	v_pk_add_f32 v[26:27], v[26:27], v[184:185]
	v_pk_add_f32 v[28:29], v[28:29], v[186:187]
	v_pk_add_f32 v[22:23], v[22:23], v[188:189]
	v_pk_add_f32 v[24:25], v[24:25], v[190:191]
	v_pk_add_f32 v[18:19], v[18:19], v[192:193]
	v_pk_add_f32 v[20:21], v[20:21], v[194:195]
	v_pk_add_f32 v[14:15], v[14:15], v[196:197]
	v_pk_add_f32 v[16:17], v[16:17], v[198:199]
	v_pk_add_f32 v[10:11], v[10:11], v[200:201]
	v_pk_add_f32 v[12:13], v[12:13], v[202:203]
	v_pk_add_f32 v[6:7], v[6:7], v[204:205]
	v_pk_add_f32 v[8:9], v[8:9], v[206:207]
	v_pk_add_f32 v[2:3], v[2:3], v[208:209]
	v_pk_add_f32 v[4:5], v[4:5], v[210:211]
	global_store_dwordx4 v[72:73], v[2:5], off offset:512
	global_store_dwordx4 v[72:73], v[6:9], off offset:576
	global_store_dwordx4 v[70:71], v[10:13], off offset:512
	global_store_dwordx4 v[70:71], v[14:17], off offset:576
	global_store_dwordx4 v[68:69], v[18:21], off offset:512
	global_store_dwordx4 v[68:69], v[22:25], off offset:576
	global_store_dwordx4 v[66:67], v[26:29], off offset:512
	global_store_dwordx4 v[66:67], v[30:33], off offset:576
	s_and_b64 vcc, exec, s[0:1]
	s_mov_b32 s8, s5
	s_mov_b32 s7, s6
	s_cbranch_vccz .LBB0_129
	s_waitcnt vmcnt(0)
	s_movk_i32 s0, 0x100
	v_cmp_gt_u32_e32 vcc, s0, v239
	s_and_saveexec_b64 s[0:1], vcc
	s_cbranch_execz .LBB0_136
	s_barrier
